# adds: .p2align 6 before the 10 GEMM K-loop headers and the two prompt attention tile-loop headers (code placement only)
# speedup vs baseline: 1.0040x; 1.0040x over previous
; template <class Epi, class Sched, bool ALIGN_EPI = false, bool SP2 = false>
; __device__ __forceinline__ void gemm_phase(PG8_LAS unsigned char* lds, const Gemm g, const Sched& S, const Epi& E, const int tid_in) {
;     ...
;     f32x4 acc[2][2][4][2];
; #pragma unroll
;     for (int a = 0; a < 2; ++a)
; #pragma unroll
;         for (int b = 0; b < 2; ++b)
; #pragma unroll
;             for (int m = 0; m < 4; ++m)
; #pragma unroll
;                 for (int n = 0; n < 2; ++n) acc[a][b][m][n] = (f32x4){0.f, 0.f, 0.f, 0.f};
;     ...
;     for (;;) {
;         const bool has_next = S.next(ui + 1, nxt);
;         const char* nA = has_next ? (const char*)g.A + (size_t)nxt.pm * tstep : cA; const char* nB = has_next ? (const char*)g.Bt + (size_t)nxt.pn * tstep : cB;
;         for (int t = 0; t < nt; t += 2) {
;             const bool last = (t == nt - 2);
;             const char* a1 = cA + (size_t)(t + 1) * kstep;
;             const char* a2 = last ? nA : cA + (size_t)(t + 2) * kstep; const char* b2 = last ? nB : cB + (size_t)(t + 2) * kstep;
;             const char* a3 = a2 + kstep; const char* b3 = b2 + kstep;
.LBB0_235:
	v_mov_b32_e32 v127, 0
	s_andn2_b64 vcc, exec, s[14:15]
	v_mov_b32_e32 v126, v127
	v_mov_b32_e32 v125, v127
	v_mov_b32_e32 v124, v127
	v_mov_b32_e32 v123, v127
	v_mov_b32_e32 v122, v127
	v_mov_b32_e32 v121, v127
	v_mov_b32_e32 v120, v127
	v_mov_b32_e32 v111, v127
	v_mov_b32_e32 v110, v127
	v_mov_b32_e32 v109, v127
	v_mov_b32_e32 v108, v127
	v_mov_b32_e32 v107, v127
	v_mov_b32_e32 v106, v127
	v_mov_b32_e32 v105, v127
	v_mov_b32_e32 v104, v127
	v_mov_b32_e32 v95, v127
	v_mov_b32_e32 v94, v127
	v_mov_b32_e32 v93, v127
	v_mov_b32_e32 v92, v127
	v_mov_b32_e32 v91, v127
	v_mov_b32_e32 v90, v127
	v_mov_b32_e32 v89, v127
	v_mov_b32_e32 v88, v127
	v_mov_b32_e32 v79, v127
	v_mov_b32_e32 v78, v127
	v_mov_b32_e32 v77, v127
	v_mov_b32_e32 v76, v127
	v_mov_b32_e32 v75, v127
	v_mov_b32_e32 v74, v127
	v_mov_b32_e32 v73, v127
	v_mov_b32_e32 v72, v127
	v_mov_b32_e32 v119, v127
	v_mov_b32_e32 v118, v127
	v_mov_b32_e32 v117, v127
	v_mov_b32_e32 v116, v127
	v_mov_b32_e32 v115, v127
	v_mov_b32_e32 v114, v127
	v_mov_b32_e32 v113, v127
	v_mov_b32_e32 v112, v127
	v_mov_b32_e32 v103, v127
	v_mov_b32_e32 v102, v127
	v_mov_b32_e32 v101, v127
	v_mov_b32_e32 v100, v127
	v_mov_b32_e32 v99, v127
	v_mov_b32_e32 v98, v127
	v_mov_b32_e32 v97, v127
	v_mov_b32_e32 v96, v127
	v_mov_b32_e32 v87, v127
	v_mov_b32_e32 v86, v127
	v_mov_b32_e32 v85, v127
	v_mov_b32_e32 v84, v127
	v_mov_b32_e32 v83, v127
	v_mov_b32_e32 v82, v127
	v_mov_b32_e32 v81, v127
	v_mov_b32_e32 v80, v127
	v_mov_b32_e32 v71, v127
	v_mov_b32_e32 v70, v127
	v_mov_b32_e32 v69, v127
	v_mov_b32_e32 v68, v127
	v_mov_b32_e32 v67, v127
	v_mov_b32_e32 v66, v127
	v_mov_b32_e32 v65, v127
	v_mov_b32_e32 v64, v127
	v_mov_b32_e32 v63, v127
	v_mov_b32_e32 v62, v127
	v_mov_b32_e32 v61, v127
	v_mov_b32_e32 v60, v127
	v_mov_b32_e32 v59, v127
	v_mov_b32_e32 v58, v127
	v_mov_b32_e32 v57, v127
	v_mov_b32_e32 v56, v127
	v_mov_b32_e32 v47, v127
	v_mov_b32_e32 v46, v127
	v_mov_b32_e32 v45, v127
	v_mov_b32_e32 v44, v127
	v_mov_b32_e32 v43, v127
	v_mov_b32_e32 v42, v127
	v_mov_b32_e32 v41, v127
	v_mov_b32_e32 v40, v127
	v_mov_b32_e32 v31, v127
	v_mov_b32_e32 v30, v127
	v_mov_b32_e32 v29, v127
	v_mov_b32_e32 v28, v127
	v_mov_b32_e32 v27, v127
	v_mov_b32_e32 v26, v127
	v_mov_b32_e32 v25, v127
	v_mov_b32_e32 v24, v127
	v_mov_b32_e32 v15, v127
	v_mov_b32_e32 v14, v127
	v_mov_b32_e32 v13, v127
	v_mov_b32_e32 v12, v127
	v_mov_b32_e32 v11, v127
	v_mov_b32_e32 v10, v127
	v_mov_b32_e32 v9, v127
	v_mov_b32_e32 v8, v127
	v_mov_b32_e32 v55, v127
	v_mov_b32_e32 v54, v127
	v_mov_b32_e32 v53, v127
	v_mov_b32_e32 v52, v127
	v_mov_b32_e32 v51, v127
	v_mov_b32_e32 v50, v127
	v_mov_b32_e32 v49, v127
	v_mov_b32_e32 v48, v127
	v_mov_b32_e32 v39, v127
	v_mov_b32_e32 v38, v127
	v_mov_b32_e32 v37, v127
	v_mov_b32_e32 v36, v127
	v_mov_b32_e32 v35, v127
	v_mov_b32_e32 v34, v127
	v_mov_b32_e32 v33, v127
	v_mov_b32_e32 v32, v127
	v_mov_b32_e32 v23, v127
	v_mov_b32_e32 v22, v127
	v_mov_b32_e32 v21, v127
	v_mov_b32_e32 v20, v127
	v_mov_b32_e32 v19, v127
	v_mov_b32_e32 v18, v127
	v_mov_b32_e32 v17, v127
	v_mov_b32_e32 v16, v127
	v_mov_b32_e32 v7, v127
	v_mov_b32_e32 v6, v127
	v_mov_b32_e32 v5, v127
	v_mov_b32_e32 v4, v127
	v_mov_b32_e32 v3, v127
	v_mov_b32_e32 v2, v127
	v_mov_b32_e32 v1, v127
	v_mov_b32_e32 v0, v127
	s_cbranch_vccnz .LBB0_239
	s_add_u32 s20, s20, 0x80
	s_addc_u32 s21, s21, 0
	s_add_u32 s49, s22, 0x100
	v_mov_b32_e32 v0, 0
	s_addc_u32 s50, s23, 0
	s_mov_b32 s22, 0
	v_mov_b32_e32 v1, v0
	v_mov_b32_e32 v2, v0
	v_mov_b32_e32 v3, v0
	v_mov_b32_e32 v4, v0
	v_mov_b32_e32 v5, v0
	v_mov_b32_e32 v6, v0
	v_mov_b32_e32 v7, v0
	v_mov_b32_e32 v16, v0
	v_mov_b32_e32 v17, v0
	v_mov_b32_e32 v18, v0
	v_mov_b32_e32 v19, v0
	v_mov_b32_e32 v20, v0
	v_mov_b32_e32 v21, v0
	v_mov_b32_e32 v22, v0
	v_mov_b32_e32 v23, v0
	v_mov_b32_e32 v32, v0
	v_mov_b32_e32 v33, v0
	v_mov_b32_e32 v34, v0
	v_mov_b32_e32 v35, v0
	v_mov_b32_e32 v36, v0
	v_mov_b32_e32 v37, v0
	v_mov_b32_e32 v38, v0
	v_mov_b32_e32 v39, v0
	v_mov_b32_e32 v48, v0
	v_mov_b32_e32 v49, v0
	v_mov_b32_e32 v50, v0
	v_mov_b32_e32 v51, v0
	v_mov_b32_e32 v52, v0
	v_mov_b32_e32 v53, v0
	v_mov_b32_e32 v54, v0
	v_mov_b32_e32 v55, v0
	v_mov_b32_e32 v8, v0
	v_mov_b32_e32 v9, v0
	v_mov_b32_e32 v10, v0
	v_mov_b32_e32 v11, v0
	v_mov_b32_e32 v12, v0
	v_mov_b32_e32 v13, v0
	v_mov_b32_e32 v14, v0
	v_mov_b32_e32 v15, v0
	v_mov_b32_e32 v24, v0
	v_mov_b32_e32 v25, v0
	v_mov_b32_e32 v26, v0
	v_mov_b32_e32 v27, v0
	v_mov_b32_e32 v28, v0
	v_mov_b32_e32 v29, v0
	v_mov_b32_e32 v30, v0
	v_mov_b32_e32 v31, v0
	v_mov_b32_e32 v40, v0
	v_mov_b32_e32 v41, v0
	v_mov_b32_e32 v42, v0
	v_mov_b32_e32 v43, v0
	v_mov_b32_e32 v44, v0
	v_mov_b32_e32 v45, v0
	v_mov_b32_e32 v46, v0
	v_mov_b32_e32 v47, v0
	v_mov_b32_e32 v56, v0
	v_mov_b32_e32 v57, v0
	v_mov_b32_e32 v58, v0
	v_mov_b32_e32 v59, v0
	v_mov_b32_e32 v60, v0
	v_mov_b32_e32 v61, v0
	v_mov_b32_e32 v62, v0
	v_mov_b32_e32 v63, v0
	v_mov_b32_e32 v64, v0
	v_mov_b32_e32 v65, v0
	v_mov_b32_e32 v66, v0
	v_mov_b32_e32 v67, v0
	v_mov_b32_e32 v68, v0
	v_mov_b32_e32 v69, v0
	v_mov_b32_e32 v70, v0
	v_mov_b32_e32 v71, v0
	v_mov_b32_e32 v80, v0
	v_mov_b32_e32 v81, v0
	v_mov_b32_e32 v82, v0
	v_mov_b32_e32 v83, v0
	v_mov_b32_e32 v84, v0
	v_mov_b32_e32 v85, v0
	v_mov_b32_e32 v86, v0
	v_mov_b32_e32 v87, v0
	v_mov_b32_e32 v96, v0
	v_mov_b32_e32 v97, v0
	v_mov_b32_e32 v98, v0
	v_mov_b32_e32 v99, v0
	v_mov_b32_e32 v100, v0
	v_mov_b32_e32 v101, v0
	v_mov_b32_e32 v102, v0
	v_mov_b32_e32 v103, v0
	v_mov_b32_e32 v112, v0
	v_mov_b32_e32 v113, v0
	v_mov_b32_e32 v114, v0
	v_mov_b32_e32 v115, v0
	v_mov_b32_e32 v116, v0
	v_mov_b32_e32 v117, v0
	v_mov_b32_e32 v118, v0
	v_mov_b32_e32 v119, v0
	v_mov_b32_e32 v72, v0
	v_mov_b32_e32 v73, v0
	v_mov_b32_e32 v74, v0
	v_mov_b32_e32 v75, v0
	v_mov_b32_e32 v76, v0
	v_mov_b32_e32 v77, v0
	v_mov_b32_e32 v78, v0
	v_mov_b32_e32 v79, v0
	v_mov_b32_e32 v88, v0
	v_mov_b32_e32 v89, v0
	v_mov_b32_e32 v90, v0
	v_mov_b32_e32 v91, v0
	v_mov_b32_e32 v92, v0
	v_mov_b32_e32 v93, v0
	v_mov_b32_e32 v94, v0
	v_mov_b32_e32 v95, v0
	v_mov_b32_e32 v104, v0
	v_mov_b32_e32 v105, v0
	v_mov_b32_e32 v106, v0
	v_mov_b32_e32 v107, v0
	v_mov_b32_e32 v108, v0
	v_mov_b32_e32 v109, v0
	v_mov_b32_e32 v110, v0
	v_mov_b32_e32 v111, v0
	v_mov_b32_e32 v120, v0
	v_mov_b32_e32 v121, v0
	v_mov_b32_e32 v122, v0
	v_mov_b32_e32 v123, v0
	v_mov_b32_e32 v124, v0
	v_mov_b32_e32 v125, v0
	v_mov_b32_e32 v126, v0
	v_mov_b32_e32 v127, v0
	.p2align	6

; template <class Epi, class Sched, bool ALIGN_EPI = false, bool SP2 = false>
; __device__ __forceinline__ void gemm_phase(PG8_LAS unsigned char* lds, const Gemm g, const Sched& S, const Epi& E, const int tid_in) {
;     ...
;     const char* cA = (const char*)g.A + (size_t)cur.pm * tstep; const char* cB = (const char*)g.Bt + (size_t)cur.pn * tstep;
;     ...
;     for (;;) {
;         const bool has_next = S.next(ui + 1, nxt);
;         const char* nA = has_next ? (const char*)g.A + (size_t)nxt.pm * tstep : cA; const char* nB = has_next ? (const char*)g.Bt + (size_t)nxt.pn * tstep : cB;
;         for (int t = 0; t < nt; t += 2) {
;             const bool last = (t == nt - 2);
;             const char* a1 = cA + (size_t)(t + 1) * kstep;
;             const char* a2 = last ? nA : cA + (size_t)(t + 2) * kstep; const char* b2 = last ? nB : cB + (size_t)(t + 2) * kstep;
;             const char* a3 = a2 + kstep; const char* b3 = b2 + kstep;
.LBB0_286:
	s_ashr_i32 s17, s16, 31
	s_lshl_b64 s[18:19], s[16:17], 21
	s_add_u32 s18, s34, s18
	s_addc_u32 s19, s35, s19
	s_ashr_i32 s15, s14, 31
	s_lshl_b64 s[20:21], s[14:15], 21
	s_add_u32 s20, s36, s20
	v_mov_b32_e32 v123, 0
	s_addc_u32 s21, s37, s21
	s_andn2_b64 vcc, exec, s[6:7]
	v_mov_b32_e32 v122, v123
	v_mov_b32_e32 v121, v123
	v_mov_b32_e32 v120, v123
	v_mov_b32_e32 v127, v123
	v_mov_b32_e32 v126, v123
	v_mov_b32_e32 v125, v123
	v_mov_b32_e32 v124, v123
	v_mov_b32_e32 v111, v123
	v_mov_b32_e32 v110, v123
	v_mov_b32_e32 v109, v123
	v_mov_b32_e32 v108, v123
	v_mov_b32_e32 v107, v123
	v_mov_b32_e32 v106, v123
	v_mov_b32_e32 v105, v123
	v_mov_b32_e32 v104, v123
	v_mov_b32_e32 v95, v123
	v_mov_b32_e32 v94, v123
	v_mov_b32_e32 v93, v123
	v_mov_b32_e32 v92, v123
	v_mov_b32_e32 v91, v123
	v_mov_b32_e32 v90, v123
	v_mov_b32_e32 v89, v123
	v_mov_b32_e32 v88, v123
	v_mov_b32_e32 v79, v123
	v_mov_b32_e32 v78, v123
	v_mov_b32_e32 v77, v123
	v_mov_b32_e32 v76, v123
	v_mov_b32_e32 v75, v123
	v_mov_b32_e32 v74, v123
	v_mov_b32_e32 v73, v123
	v_mov_b32_e32 v72, v123
	v_mov_b32_e32 v119, v123
	v_mov_b32_e32 v118, v123
	v_mov_b32_e32 v117, v123
	v_mov_b32_e32 v116, v123
	v_mov_b32_e32 v115, v123
	v_mov_b32_e32 v114, v123
	v_mov_b32_e32 v113, v123
	v_mov_b32_e32 v112, v123
	v_mov_b32_e32 v103, v123
	v_mov_b32_e32 v102, v123
	v_mov_b32_e32 v101, v123
	v_mov_b32_e32 v100, v123
	v_mov_b32_e32 v99, v123
	v_mov_b32_e32 v98, v123
	v_mov_b32_e32 v97, v123
	v_mov_b32_e32 v96, v123
	v_mov_b32_e32 v87, v123
	v_mov_b32_e32 v86, v123
	v_mov_b32_e32 v85, v123
	v_mov_b32_e32 v84, v123
	v_mov_b32_e32 v83, v123
	v_mov_b32_e32 v82, v123
	v_mov_b32_e32 v81, v123
	v_mov_b32_e32 v80, v123
	v_mov_b32_e32 v71, v123
	v_mov_b32_e32 v70, v123
	v_mov_b32_e32 v69, v123
	v_mov_b32_e32 v68, v123
	v_mov_b32_e32 v67, v123
	v_mov_b32_e32 v66, v123
	v_mov_b32_e32 v65, v123
	v_mov_b32_e32 v64, v123
	v_mov_b32_e32 v63, v123
	v_mov_b32_e32 v62, v123
	v_mov_b32_e32 v61, v123
	v_mov_b32_e32 v60, v123
	v_mov_b32_e32 v59, v123
	v_mov_b32_e32 v58, v123
	v_mov_b32_e32 v57, v123
	v_mov_b32_e32 v56, v123
	v_mov_b32_e32 v47, v123
	v_mov_b32_e32 v46, v123
	v_mov_b32_e32 v45, v123
	v_mov_b32_e32 v44, v123
	v_mov_b32_e32 v43, v123
	v_mov_b32_e32 v42, v123
	v_mov_b32_e32 v41, v123
	v_mov_b32_e32 v40, v123
	v_mov_b32_e32 v31, v123
	v_mov_b32_e32 v30, v123
	v_mov_b32_e32 v29, v123
	v_mov_b32_e32 v28, v123
	v_mov_b32_e32 v27, v123
	v_mov_b32_e32 v26, v123
	v_mov_b32_e32 v25, v123
	v_mov_b32_e32 v24, v123
	v_mov_b32_e32 v15, v123
	v_mov_b32_e32 v14, v123
	v_mov_b32_e32 v13, v123
	v_mov_b32_e32 v12, v123
	v_mov_b32_e32 v11, v123
	v_mov_b32_e32 v10, v123
	v_mov_b32_e32 v9, v123
	v_mov_b32_e32 v8, v123
	v_mov_b32_e32 v55, v123
	v_mov_b32_e32 v54, v123
	v_mov_b32_e32 v53, v123
	v_mov_b32_e32 v52, v123
	v_mov_b32_e32 v51, v123
	v_mov_b32_e32 v50, v123
	v_mov_b32_e32 v49, v123
	v_mov_b32_e32 v48, v123
	v_mov_b32_e32 v39, v123
	v_mov_b32_e32 v38, v123
	v_mov_b32_e32 v37, v123
	v_mov_b32_e32 v36, v123
	v_mov_b32_e32 v35, v123
	v_mov_b32_e32 v34, v123
	v_mov_b32_e32 v33, v123
	v_mov_b32_e32 v32, v123
	v_mov_b32_e32 v23, v123
	v_mov_b32_e32 v22, v123
	v_mov_b32_e32 v21, v123
	v_mov_b32_e32 v20, v123
	v_mov_b32_e32 v19, v123
	v_mov_b32_e32 v18, v123
	v_mov_b32_e32 v17, v123
	v_mov_b32_e32 v16, v123
	v_mov_b32_e32 v7, v123
	v_mov_b32_e32 v6, v123
	v_mov_b32_e32 v5, v123
	v_mov_b32_e32 v4, v123
	v_mov_b32_e32 v3, v123
	v_mov_b32_e32 v2, v123
	v_mov_b32_e32 v1, v123
	v_mov_b32_e32 v0, v123
	s_cbranch_vccnz .LBB0_289
	s_and_b64 s[26:27], s[0:1], exec
	s_cselect_b32 s11, s19, s23
	s_cselect_b32 s13, s18, s22
	s_cselect_b32 s15, s21, s25
	s_cselect_b32 s17, s20, s24
	s_add_u32 s22, s22, 0x100080
	s_addc_u32 s23, s23, 0
	s_add_u32 s54, s24, 0x100
	v_mov_b32_e32 v0, 0
	s_addc_u32 s55, s25, 0
	s_mov_b32 s24, 0
	v_mov_b32_e32 v1, v0
	v_mov_b32_e32 v2, v0
	v_mov_b32_e32 v3, v0
	v_mov_b32_e32 v4, v0
	v_mov_b32_e32 v5, v0
	v_mov_b32_e32 v6, v0
	v_mov_b32_e32 v7, v0
	v_mov_b32_e32 v16, v0
	v_mov_b32_e32 v17, v0
	v_mov_b32_e32 v18, v0
	v_mov_b32_e32 v19, v0
	v_mov_b32_e32 v20, v0
	v_mov_b32_e32 v21, v0
	v_mov_b32_e32 v22, v0
	v_mov_b32_e32 v23, v0
	v_mov_b32_e32 v32, v0
	v_mov_b32_e32 v33, v0
	v_mov_b32_e32 v34, v0
	v_mov_b32_e32 v35, v0
	v_mov_b32_e32 v36, v0
	v_mov_b32_e32 v37, v0
	v_mov_b32_e32 v38, v0
	v_mov_b32_e32 v39, v0
	v_mov_b32_e32 v48, v0
	v_mov_b32_e32 v49, v0
	v_mov_b32_e32 v50, v0
	v_mov_b32_e32 v51, v0
	v_mov_b32_e32 v52, v0
	v_mov_b32_e32 v53, v0
	v_mov_b32_e32 v54, v0
	v_mov_b32_e32 v55, v0
	v_mov_b32_e32 v8, v0
	v_mov_b32_e32 v9, v0
	v_mov_b32_e32 v10, v0
	v_mov_b32_e32 v11, v0
	v_mov_b32_e32 v12, v0
	v_mov_b32_e32 v13, v0
	v_mov_b32_e32 v14, v0
	v_mov_b32_e32 v15, v0
	v_mov_b32_e32 v24, v0
	v_mov_b32_e32 v25, v0
	v_mov_b32_e32 v26, v0
	v_mov_b32_e32 v27, v0
	v_mov_b32_e32 v28, v0
	v_mov_b32_e32 v29, v0
	v_mov_b32_e32 v30, v0
	v_mov_b32_e32 v31, v0
	v_mov_b32_e32 v40, v0
	v_mov_b32_e32 v41, v0
	v_mov_b32_e32 v42, v0
	v_mov_b32_e32 v43, v0
	v_mov_b32_e32 v44, v0
	v_mov_b32_e32 v45, v0
	v_mov_b32_e32 v46, v0
	v_mov_b32_e32 v47, v0
	v_mov_b32_e32 v56, v0
	v_mov_b32_e32 v57, v0
	v_mov_b32_e32 v58, v0
	v_mov_b32_e32 v59, v0
	v_mov_b32_e32 v60, v0
	v_mov_b32_e32 v61, v0
	v_mov_b32_e32 v62, v0
	v_mov_b32_e32 v63, v0
	v_mov_b32_e32 v64, v0
	v_mov_b32_e32 v65, v0
	v_mov_b32_e32 v66, v0
	v_mov_b32_e32 v67, v0
	v_mov_b32_e32 v68, v0
	v_mov_b32_e32 v69, v0
	v_mov_b32_e32 v70, v0
	v_mov_b32_e32 v71, v0
	v_mov_b32_e32 v80, v0
	v_mov_b32_e32 v81, v0
	v_mov_b32_e32 v82, v0
	v_mov_b32_e32 v83, v0
	v_mov_b32_e32 v84, v0
	v_mov_b32_e32 v85, v0
	v_mov_b32_e32 v86, v0
	v_mov_b32_e32 v87, v0
	v_mov_b32_e32 v96, v0
	v_mov_b32_e32 v97, v0
	v_mov_b32_e32 v98, v0
	v_mov_b32_e32 v99, v0
	v_mov_b32_e32 v100, v0
	v_mov_b32_e32 v101, v0
	v_mov_b32_e32 v102, v0
	v_mov_b32_e32 v103, v0
	v_mov_b32_e32 v112, v0
	v_mov_b32_e32 v113, v0
	v_mov_b32_e32 v114, v0
	v_mov_b32_e32 v115, v0
	v_mov_b32_e32 v116, v0
	v_mov_b32_e32 v117, v0
	v_mov_b32_e32 v118, v0
	v_mov_b32_e32 v119, v0
	v_mov_b32_e32 v72, v0
	v_mov_b32_e32 v73, v0
	v_mov_b32_e32 v74, v0
	v_mov_b32_e32 v75, v0
	v_mov_b32_e32 v76, v0
	v_mov_b32_e32 v77, v0
	v_mov_b32_e32 v78, v0
	v_mov_b32_e32 v79, v0
	v_mov_b32_e32 v88, v0
	v_mov_b32_e32 v89, v0
	v_mov_b32_e32 v90, v0
	v_mov_b32_e32 v91, v0
	v_mov_b32_e32 v92, v0
	v_mov_b32_e32 v93, v0
	v_mov_b32_e32 v94, v0
	v_mov_b32_e32 v95, v0
	v_mov_b32_e32 v104, v0
	v_mov_b32_e32 v105, v0
	v_mov_b32_e32 v106, v0
	v_mov_b32_e32 v107, v0
	v_mov_b32_e32 v108, v0
	v_mov_b32_e32 v109, v0
	v_mov_b32_e32 v110, v0
	v_mov_b32_e32 v111, v0
	v_mov_b32_e32 v124, v0
	v_mov_b32_e32 v125, v0
	v_mov_b32_e32 v126, v0
	v_mov_b32_e32 v127, v0
	v_mov_b32_e32 v120, v0
	v_mov_b32_e32 v121, v0
	v_mov_b32_e32 v122, v0
	v_mov_b32_e32 v123, v0
	.p2align	6

; template <class Epi, class Sched, bool ALIGN_EPI = false, bool SP2 = false>
; __device__ __forceinline__ void gemm_phase(PG8_LAS unsigned char* lds, const Gemm g, const Sched& S, const Epi& E, const int tid_in) {
;     ...
;     f32x4 acc[2][2][4][2];
; #pragma unroll
;     for (int a = 0; a < 2; ++a)
; #pragma unroll
;         for (int b = 0; b < 2; ++b)
; #pragma unroll
;             for (int m = 0; m < 4; ++m)
; #pragma unroll
;                 for (int n = 0; n < 2; ++n) acc[a][b][m][n] = (f32x4){0.f, 0.f, 0.f, 0.f};
;     ...
;     for (;;) {
;         const bool has_next = S.next(ui + 1, nxt);
;         const char* nA = has_next ? (const char*)g.A + (size_t)nxt.pm * tstep : cA; const char* nB = has_next ? (const char*)g.Bt + (size_t)nxt.pn * tstep : cB;
;         for (int t = 0; t < nt; t += 2) {
;             const bool last = (t == nt - 2);
;             const char* a1 = cA + (size_t)(t + 1) * kstep;
;             const char* a2 = last ? nA : cA + (size_t)(t + 2) * kstep; const char* b2 = last ? nB : cB + (size_t)(t + 2) * kstep;
;             const char* a3 = a2 + kstep; const char* b3 = b2 + kstep;
.LBB0_327:
	v_mov_b32_e32 v127, 0
	s_andn2_b64 vcc, exec, s[20:21]
	v_mov_b32_e32 v126, v127
	v_mov_b32_e32 v125, v127
	v_mov_b32_e32 v124, v127
	v_mov_b32_e32 v123, v127
	v_mov_b32_e32 v122, v127
	v_mov_b32_e32 v121, v127
	v_mov_b32_e32 v120, v127
	v_mov_b32_e32 v111, v127
	v_mov_b32_e32 v110, v127
	v_mov_b32_e32 v109, v127
	v_mov_b32_e32 v108, v127
	v_mov_b32_e32 v107, v127
	v_mov_b32_e32 v106, v127
	v_mov_b32_e32 v105, v127
	v_mov_b32_e32 v104, v127
	v_mov_b32_e32 v95, v127
	v_mov_b32_e32 v94, v127
	v_mov_b32_e32 v93, v127
	v_mov_b32_e32 v92, v127
	v_mov_b32_e32 v91, v127
	v_mov_b32_e32 v90, v127
	v_mov_b32_e32 v89, v127
	v_mov_b32_e32 v88, v127
	v_mov_b32_e32 v79, v127
	v_mov_b32_e32 v78, v127
	v_mov_b32_e32 v77, v127
	v_mov_b32_e32 v76, v127
	v_mov_b32_e32 v75, v127
	v_mov_b32_e32 v74, v127
	v_mov_b32_e32 v73, v127
	v_mov_b32_e32 v72, v127
	v_mov_b32_e32 v119, v127
	v_mov_b32_e32 v118, v127
	v_mov_b32_e32 v117, v127
	v_mov_b32_e32 v116, v127
	v_mov_b32_e32 v115, v127
	v_mov_b32_e32 v114, v127
	v_mov_b32_e32 v113, v127
	v_mov_b32_e32 v112, v127
	v_mov_b32_e32 v103, v127
	v_mov_b32_e32 v102, v127
	v_mov_b32_e32 v101, v127
	v_mov_b32_e32 v100, v127
	v_mov_b32_e32 v99, v127
	v_mov_b32_e32 v98, v127
	v_mov_b32_e32 v97, v127
	v_mov_b32_e32 v96, v127
	v_mov_b32_e32 v87, v127
	v_mov_b32_e32 v86, v127
	v_mov_b32_e32 v85, v127
	v_mov_b32_e32 v84, v127
	v_mov_b32_e32 v83, v127
	v_mov_b32_e32 v82, v127
	v_mov_b32_e32 v81, v127
	v_mov_b32_e32 v80, v127
	v_mov_b32_e32 v71, v127
	v_mov_b32_e32 v70, v127
	v_mov_b32_e32 v69, v127
	v_mov_b32_e32 v68, v127
	v_mov_b32_e32 v67, v127
	v_mov_b32_e32 v66, v127
	v_mov_b32_e32 v65, v127
	v_mov_b32_e32 v64, v127
	v_mov_b32_e32 v63, v127
	v_mov_b32_e32 v62, v127
	v_mov_b32_e32 v61, v127
	v_mov_b32_e32 v60, v127
	v_mov_b32_e32 v59, v127
	v_mov_b32_e32 v58, v127
	v_mov_b32_e32 v57, v127
	v_mov_b32_e32 v56, v127
	v_mov_b32_e32 v47, v127
	v_mov_b32_e32 v46, v127
	v_mov_b32_e32 v45, v127
	v_mov_b32_e32 v44, v127
	v_mov_b32_e32 v43, v127
	v_mov_b32_e32 v42, v127
	v_mov_b32_e32 v41, v127
	v_mov_b32_e32 v40, v127
	v_mov_b32_e32 v31, v127
	v_mov_b32_e32 v30, v127
	v_mov_b32_e32 v29, v127
	v_mov_b32_e32 v28, v127
	v_mov_b32_e32 v27, v127
	v_mov_b32_e32 v26, v127
	v_mov_b32_e32 v25, v127
	v_mov_b32_e32 v24, v127
	v_mov_b32_e32 v15, v127
	v_mov_b32_e32 v14, v127
	v_mov_b32_e32 v13, v127
	v_mov_b32_e32 v12, v127
	v_mov_b32_e32 v11, v127
	v_mov_b32_e32 v10, v127
	v_mov_b32_e32 v9, v127
	v_mov_b32_e32 v8, v127
	v_mov_b32_e32 v55, v127
	v_mov_b32_e32 v54, v127
	v_mov_b32_e32 v53, v127
	v_mov_b32_e32 v52, v127
	v_mov_b32_e32 v51, v127
	v_mov_b32_e32 v50, v127
	v_mov_b32_e32 v49, v127
	v_mov_b32_e32 v48, v127
	v_mov_b32_e32 v39, v127
	v_mov_b32_e32 v38, v127
	v_mov_b32_e32 v37, v127
	v_mov_b32_e32 v36, v127
	v_mov_b32_e32 v35, v127
	v_mov_b32_e32 v34, v127
	v_mov_b32_e32 v33, v127
	v_mov_b32_e32 v32, v127
	v_mov_b32_e32 v23, v127
	v_mov_b32_e32 v22, v127
	v_mov_b32_e32 v21, v127
	v_mov_b32_e32 v20, v127
	v_mov_b32_e32 v19, v127
	v_mov_b32_e32 v18, v127
	v_mov_b32_e32 v17, v127
	v_mov_b32_e32 v16, v127
	v_mov_b32_e32 v7, v127
	v_mov_b32_e32 v6, v127
	v_mov_b32_e32 v5, v127
	v_mov_b32_e32 v4, v127
	v_mov_b32_e32 v3, v127
	v_mov_b32_e32 v2, v127
	v_mov_b32_e32 v1, v127
	v_mov_b32_e32 v0, v127
	s_cbranch_vccnz .LBB0_331
	s_add_u32 s26, s26, 0x80
	s_addc_u32 s27, s27, 0
	s_add_u32 s59, s28, 0x100
	v_mov_b32_e32 v0, 0
	s_addc_u32 s60, s29, 0
	s_mov_b32 s28, 0
	v_mov_b32_e32 v1, v0
	v_mov_b32_e32 v2, v0
	v_mov_b32_e32 v3, v0
	v_mov_b32_e32 v4, v0
	v_mov_b32_e32 v5, v0
	v_mov_b32_e32 v6, v0
	v_mov_b32_e32 v7, v0
	v_mov_b32_e32 v16, v0
	v_mov_b32_e32 v17, v0
	v_mov_b32_e32 v18, v0
	v_mov_b32_e32 v19, v0
	v_mov_b32_e32 v20, v0
	v_mov_b32_e32 v21, v0
	v_mov_b32_e32 v22, v0
	v_mov_b32_e32 v23, v0
	v_mov_b32_e32 v32, v0
	v_mov_b32_e32 v33, v0
	v_mov_b32_e32 v34, v0
	v_mov_b32_e32 v35, v0
	v_mov_b32_e32 v36, v0
	v_mov_b32_e32 v37, v0
	v_mov_b32_e32 v38, v0
	v_mov_b32_e32 v39, v0
	v_mov_b32_e32 v48, v0
	v_mov_b32_e32 v49, v0
	v_mov_b32_e32 v50, v0
	v_mov_b32_e32 v51, v0
	v_mov_b32_e32 v52, v0
	v_mov_b32_e32 v53, v0
	v_mov_b32_e32 v54, v0
	v_mov_b32_e32 v55, v0
	v_mov_b32_e32 v8, v0
	v_mov_b32_e32 v9, v0
	v_mov_b32_e32 v10, v0
	v_mov_b32_e32 v11, v0
	v_mov_b32_e32 v12, v0
	v_mov_b32_e32 v13, v0
	v_mov_b32_e32 v14, v0
	v_mov_b32_e32 v15, v0
	v_mov_b32_e32 v24, v0
	v_mov_b32_e32 v25, v0
	v_mov_b32_e32 v26, v0
	v_mov_b32_e32 v27, v0
	v_mov_b32_e32 v28, v0
	v_mov_b32_e32 v29, v0
	v_mov_b32_e32 v30, v0
	v_mov_b32_e32 v31, v0
	v_mov_b32_e32 v40, v0
	v_mov_b32_e32 v41, v0
	v_mov_b32_e32 v42, v0
	v_mov_b32_e32 v43, v0
	v_mov_b32_e32 v44, v0
	v_mov_b32_e32 v45, v0
	v_mov_b32_e32 v46, v0
	v_mov_b32_e32 v47, v0
	v_mov_b32_e32 v56, v0
	v_mov_b32_e32 v57, v0
	v_mov_b32_e32 v58, v0
	v_mov_b32_e32 v59, v0
	v_mov_b32_e32 v60, v0
	v_mov_b32_e32 v61, v0
	v_mov_b32_e32 v62, v0
	v_mov_b32_e32 v63, v0
	v_mov_b32_e32 v64, v0
	v_mov_b32_e32 v65, v0
	v_mov_b32_e32 v66, v0
	v_mov_b32_e32 v67, v0
	v_mov_b32_e32 v68, v0
	v_mov_b32_e32 v69, v0
	v_mov_b32_e32 v70, v0
	v_mov_b32_e32 v71, v0
	v_mov_b32_e32 v80, v0
	v_mov_b32_e32 v81, v0
	v_mov_b32_e32 v82, v0
	v_mov_b32_e32 v83, v0
	v_mov_b32_e32 v84, v0
	v_mov_b32_e32 v85, v0
	v_mov_b32_e32 v86, v0
	v_mov_b32_e32 v87, v0
	v_mov_b32_e32 v96, v0
	v_mov_b32_e32 v97, v0
	v_mov_b32_e32 v98, v0
	v_mov_b32_e32 v99, v0
	v_mov_b32_e32 v100, v0
	v_mov_b32_e32 v101, v0
	v_mov_b32_e32 v102, v0
	v_mov_b32_e32 v103, v0
	v_mov_b32_e32 v112, v0
	v_mov_b32_e32 v113, v0
	v_mov_b32_e32 v114, v0
	v_mov_b32_e32 v115, v0
	v_mov_b32_e32 v116, v0
	v_mov_b32_e32 v117, v0
	v_mov_b32_e32 v118, v0
	v_mov_b32_e32 v119, v0
	v_mov_b32_e32 v72, v0
	v_mov_b32_e32 v73, v0
	v_mov_b32_e32 v74, v0
	v_mov_b32_e32 v75, v0
	v_mov_b32_e32 v76, v0
	v_mov_b32_e32 v77, v0
	v_mov_b32_e32 v78, v0
	v_mov_b32_e32 v79, v0
	v_mov_b32_e32 v88, v0
	v_mov_b32_e32 v89, v0
	v_mov_b32_e32 v90, v0
	v_mov_b32_e32 v91, v0
	v_mov_b32_e32 v92, v0
	v_mov_b32_e32 v93, v0
	v_mov_b32_e32 v94, v0
	v_mov_b32_e32 v95, v0
	v_mov_b32_e32 v104, v0
	v_mov_b32_e32 v105, v0
	v_mov_b32_e32 v106, v0
	v_mov_b32_e32 v107, v0
	v_mov_b32_e32 v108, v0
	v_mov_b32_e32 v109, v0
	v_mov_b32_e32 v110, v0
	v_mov_b32_e32 v111, v0
	v_mov_b32_e32 v120, v0
	v_mov_b32_e32 v121, v0
	v_mov_b32_e32 v122, v0
	v_mov_b32_e32 v123, v0
	v_mov_b32_e32 v124, v0
	v_mov_b32_e32 v125, v0
	v_mov_b32_e32 v126, v0
	v_mov_b32_e32 v127, v0
	.p2align	6

; template <class Epi, class Sched, bool ALIGN_EPI = false, bool SP2 = false>
; __device__ __forceinline__ void gemm_phase(PG8_LAS unsigned char* lds, const Gemm g, const Sched& S, const Epi& E, const int tid_in) {
;     ...
;     f32x4 acc[2][2][4][2];
; #pragma unroll
;     for (int a = 0; a < 2; ++a)
; #pragma unroll
;         for (int b = 0; b < 2; ++b)
; #pragma unroll
;             for (int m = 0; m < 4; ++m)
; #pragma unroll
;                 for (int n = 0; n < 2; ++n) acc[a][b][m][n] = (f32x4){0.f, 0.f, 0.f, 0.f};
;     ...
;     for (;;) {
;         const bool has_next = S.next(ui + 1, nxt);
;         const char* nA = has_next ? (const char*)g.A + (size_t)nxt.pm * tstep : cA; const char* nB = has_next ? (const char*)g.Bt + (size_t)nxt.pn * tstep : cB;
;         for (int t = 0; t < nt; t += 2) {
;             const bool last = (t == nt - 2);
;             const char* a1 = cA + (size_t)(t + 1) * kstep;
;             const char* a2 = last ? nA : cA + (size_t)(t + 2) * kstep; const char* b2 = last ? nB : cB + (size_t)(t + 2) * kstep;
;             const char* a3 = a2 + kstep; const char* b3 = b2 + kstep;
.LBB0_377:
	v_mov_b32_e32 v127, 0
	s_andn2_b64 vcc, exec, s[18:19]
	v_mov_b32_e32 v126, v127
	v_mov_b32_e32 v125, v127
	v_mov_b32_e32 v124, v127
	v_mov_b32_e32 v123, v127
	v_mov_b32_e32 v122, v127
	v_mov_b32_e32 v121, v127
	v_mov_b32_e32 v120, v127
	v_mov_b32_e32 v111, v127
	v_mov_b32_e32 v110, v127
	v_mov_b32_e32 v109, v127
	v_mov_b32_e32 v108, v127
	v_mov_b32_e32 v107, v127
	v_mov_b32_e32 v106, v127
	v_mov_b32_e32 v105, v127
	v_mov_b32_e32 v104, v127
	v_mov_b32_e32 v95, v127
	v_mov_b32_e32 v94, v127
	v_mov_b32_e32 v93, v127
	v_mov_b32_e32 v92, v127
	v_mov_b32_e32 v91, v127
	v_mov_b32_e32 v90, v127
	v_mov_b32_e32 v89, v127
	v_mov_b32_e32 v88, v127
	v_mov_b32_e32 v79, v127
	v_mov_b32_e32 v78, v127
	v_mov_b32_e32 v77, v127
	v_mov_b32_e32 v76, v127
	v_mov_b32_e32 v75, v127
	v_mov_b32_e32 v74, v127
	v_mov_b32_e32 v73, v127
	v_mov_b32_e32 v72, v127
	v_mov_b32_e32 v119, v127
	v_mov_b32_e32 v118, v127
	v_mov_b32_e32 v117, v127
	v_mov_b32_e32 v116, v127
	v_mov_b32_e32 v115, v127
	v_mov_b32_e32 v114, v127
	v_mov_b32_e32 v113, v127
	v_mov_b32_e32 v112, v127
	v_mov_b32_e32 v103, v127
	v_mov_b32_e32 v102, v127
	v_mov_b32_e32 v101, v127
	v_mov_b32_e32 v100, v127
	v_mov_b32_e32 v99, v127
	v_mov_b32_e32 v98, v127
	v_mov_b32_e32 v97, v127
	v_mov_b32_e32 v96, v127
	v_mov_b32_e32 v87, v127
	v_mov_b32_e32 v86, v127
	v_mov_b32_e32 v85, v127
	v_mov_b32_e32 v84, v127
	v_mov_b32_e32 v83, v127
	v_mov_b32_e32 v82, v127
	v_mov_b32_e32 v81, v127
	v_mov_b32_e32 v80, v127
	v_mov_b32_e32 v71, v127
	v_mov_b32_e32 v70, v127
	v_mov_b32_e32 v69, v127
	v_mov_b32_e32 v68, v127
	v_mov_b32_e32 v67, v127
	v_mov_b32_e32 v66, v127
	v_mov_b32_e32 v65, v127
	v_mov_b32_e32 v64, v127
	v_mov_b32_e32 v63, v127
	v_mov_b32_e32 v62, v127
	v_mov_b32_e32 v61, v127
	v_mov_b32_e32 v60, v127
	v_mov_b32_e32 v59, v127
	v_mov_b32_e32 v58, v127
	v_mov_b32_e32 v57, v127
	v_mov_b32_e32 v56, v127
	v_mov_b32_e32 v47, v127
	v_mov_b32_e32 v46, v127
	v_mov_b32_e32 v45, v127
	v_mov_b32_e32 v44, v127
	v_mov_b32_e32 v43, v127
	v_mov_b32_e32 v42, v127
	v_mov_b32_e32 v41, v127
	v_mov_b32_e32 v40, v127
	v_mov_b32_e32 v31, v127
	v_mov_b32_e32 v30, v127
	v_mov_b32_e32 v29, v127
	v_mov_b32_e32 v28, v127
	v_mov_b32_e32 v27, v127
	v_mov_b32_e32 v26, v127
	v_mov_b32_e32 v25, v127
	v_mov_b32_e32 v24, v127
	v_mov_b32_e32 v15, v127
	v_mov_b32_e32 v14, v127
	v_mov_b32_e32 v13, v127
	v_mov_b32_e32 v12, v127
	v_mov_b32_e32 v11, v127
	v_mov_b32_e32 v10, v127
	v_mov_b32_e32 v9, v127
	v_mov_b32_e32 v8, v127
	v_mov_b32_e32 v55, v127
	v_mov_b32_e32 v54, v127
	v_mov_b32_e32 v53, v127
	v_mov_b32_e32 v52, v127
	v_mov_b32_e32 v51, v127
	v_mov_b32_e32 v50, v127
	v_mov_b32_e32 v49, v127
	v_mov_b32_e32 v48, v127
	v_mov_b32_e32 v39, v127
	v_mov_b32_e32 v38, v127
	v_mov_b32_e32 v37, v127
	v_mov_b32_e32 v36, v127
	v_mov_b32_e32 v35, v127
	v_mov_b32_e32 v34, v127
	v_mov_b32_e32 v33, v127
	v_mov_b32_e32 v32, v127
	v_mov_b32_e32 v23, v127
	v_mov_b32_e32 v22, v127
	v_mov_b32_e32 v21, v127
	v_mov_b32_e32 v20, v127
	v_mov_b32_e32 v19, v127
	v_mov_b32_e32 v18, v127
	v_mov_b32_e32 v17, v127
	v_mov_b32_e32 v16, v127
	v_mov_b32_e32 v7, v127
	v_mov_b32_e32 v6, v127
	v_mov_b32_e32 v5, v127
	v_mov_b32_e32 v4, v127
	v_mov_b32_e32 v3, v127
	v_mov_b32_e32 v2, v127
	v_mov_b32_e32 v1, v127
	v_mov_b32_e32 v0, v127
	s_cbranch_vccnz .LBB0_381
	s_add_u32 s24, s24, 0x80
	s_addc_u32 s25, s25, 0
	s_add_u32 s55, s26, 0x100
	v_mov_b32_e32 v0, 0
	s_addc_u32 s56, s27, 0
	s_mov_b32 s26, 0
	v_mov_b32_e32 v1, v0
	v_mov_b32_e32 v2, v0
	v_mov_b32_e32 v3, v0
	v_mov_b32_e32 v4, v0
	v_mov_b32_e32 v5, v0
	v_mov_b32_e32 v6, v0
	v_mov_b32_e32 v7, v0
	v_mov_b32_e32 v16, v0
	v_mov_b32_e32 v17, v0
	v_mov_b32_e32 v18, v0
	v_mov_b32_e32 v19, v0
	v_mov_b32_e32 v20, v0
	v_mov_b32_e32 v21, v0
	v_mov_b32_e32 v22, v0
	v_mov_b32_e32 v23, v0
	v_mov_b32_e32 v32, v0
	v_mov_b32_e32 v33, v0
	v_mov_b32_e32 v34, v0
	v_mov_b32_e32 v35, v0
	v_mov_b32_e32 v36, v0
	v_mov_b32_e32 v37, v0
	v_mov_b32_e32 v38, v0
	v_mov_b32_e32 v39, v0
	v_mov_b32_e32 v48, v0
	v_mov_b32_e32 v49, v0
	v_mov_b32_e32 v50, v0
	v_mov_b32_e32 v51, v0
	v_mov_b32_e32 v52, v0
	v_mov_b32_e32 v53, v0
	v_mov_b32_e32 v54, v0
	v_mov_b32_e32 v55, v0
	v_mov_b32_e32 v8, v0
	v_mov_b32_e32 v9, v0
	v_mov_b32_e32 v10, v0
	v_mov_b32_e32 v11, v0
	v_mov_b32_e32 v12, v0
	v_mov_b32_e32 v13, v0
	v_mov_b32_e32 v14, v0
	v_mov_b32_e32 v15, v0
	v_mov_b32_e32 v24, v0
	v_mov_b32_e32 v25, v0
	v_mov_b32_e32 v26, v0
	v_mov_b32_e32 v27, v0
	v_mov_b32_e32 v28, v0
	v_mov_b32_e32 v29, v0
	v_mov_b32_e32 v30, v0
	v_mov_b32_e32 v31, v0
	v_mov_b32_e32 v40, v0
	v_mov_b32_e32 v41, v0
	v_mov_b32_e32 v42, v0
	v_mov_b32_e32 v43, v0
	v_mov_b32_e32 v44, v0
	v_mov_b32_e32 v45, v0
	v_mov_b32_e32 v46, v0
	v_mov_b32_e32 v47, v0
	v_mov_b32_e32 v56, v0
	v_mov_b32_e32 v57, v0
	v_mov_b32_e32 v58, v0
	v_mov_b32_e32 v59, v0
	v_mov_b32_e32 v60, v0
	v_mov_b32_e32 v61, v0
	v_mov_b32_e32 v62, v0
	v_mov_b32_e32 v63, v0
	v_mov_b32_e32 v64, v0
	v_mov_b32_e32 v65, v0
	v_mov_b32_e32 v66, v0
	v_mov_b32_e32 v67, v0
	v_mov_b32_e32 v68, v0
	v_mov_b32_e32 v69, v0
	v_mov_b32_e32 v70, v0
	v_mov_b32_e32 v71, v0
	v_mov_b32_e32 v80, v0
	v_mov_b32_e32 v81, v0
	v_mov_b32_e32 v82, v0
	v_mov_b32_e32 v83, v0
	v_mov_b32_e32 v84, v0
	v_mov_b32_e32 v85, v0
	v_mov_b32_e32 v86, v0
	v_mov_b32_e32 v87, v0
	v_mov_b32_e32 v96, v0
	v_mov_b32_e32 v97, v0
	v_mov_b32_e32 v98, v0
	v_mov_b32_e32 v99, v0
	v_mov_b32_e32 v100, v0
	v_mov_b32_e32 v101, v0
	v_mov_b32_e32 v102, v0
	v_mov_b32_e32 v103, v0
	v_mov_b32_e32 v112, v0
	v_mov_b32_e32 v113, v0
	v_mov_b32_e32 v114, v0
	v_mov_b32_e32 v115, v0
	v_mov_b32_e32 v116, v0
	v_mov_b32_e32 v117, v0
	v_mov_b32_e32 v118, v0
	v_mov_b32_e32 v119, v0
	v_mov_b32_e32 v72, v0
	v_mov_b32_e32 v73, v0
	v_mov_b32_e32 v74, v0
	v_mov_b32_e32 v75, v0
	v_mov_b32_e32 v76, v0
	v_mov_b32_e32 v77, v0
	v_mov_b32_e32 v78, v0
	v_mov_b32_e32 v79, v0
	v_mov_b32_e32 v88, v0
	v_mov_b32_e32 v89, v0
	v_mov_b32_e32 v90, v0
	v_mov_b32_e32 v91, v0
	v_mov_b32_e32 v92, v0
	v_mov_b32_e32 v93, v0
	v_mov_b32_e32 v94, v0
	v_mov_b32_e32 v95, v0
	v_mov_b32_e32 v104, v0
	v_mov_b32_e32 v105, v0
	v_mov_b32_e32 v106, v0
	v_mov_b32_e32 v107, v0
	v_mov_b32_e32 v108, v0
	v_mov_b32_e32 v109, v0
	v_mov_b32_e32 v110, v0
	v_mov_b32_e32 v111, v0
	v_mov_b32_e32 v120, v0
	v_mov_b32_e32 v121, v0
	v_mov_b32_e32 v122, v0
	v_mov_b32_e32 v123, v0
	v_mov_b32_e32 v124, v0
	v_mov_b32_e32 v125, v0
	v_mov_b32_e32 v126, v0
	v_mov_b32_e32 v127, v0
	.p2align	6

; template <class Epi, class Sched, bool ALIGN_EPI = false, bool SP2 = false>
; __device__ __forceinline__ void gemm_phase(PG8_LAS unsigned char* lds, const Gemm g, const Sched& S, const Epi& E, const int tid_in) {
;     ...
;     f32x4 acc[2][2][4][2];
; #pragma unroll
;     for (int a = 0; a < 2; ++a)
; #pragma unroll
;         for (int b = 0; b < 2; ++b)
; #pragma unroll
;             for (int m = 0; m < 4; ++m)
; #pragma unroll
;                 for (int n = 0; n < 2; ++n) acc[a][b][m][n] = (f32x4){0.f, 0.f, 0.f, 0.f};
;     ...
;     for (;;) {
;         const bool has_next = S.next(ui + 1, nxt);
;         const char* nA = has_next ? (const char*)g.A + (size_t)nxt.pm * tstep : cA; const char* nB = has_next ? (const char*)g.Bt + (size_t)nxt.pn * tstep : cB;
;         for (int t = 0; t < nt; t += 2) {
;             const bool last = (t == nt - 2);
;             const char* a1 = cA + (size_t)(t + 1) * kstep;
;             const char* a2 = last ? nA : cA + (size_t)(t + 2) * kstep; const char* b2 = last ? nB : cB + (size_t)(t + 2) * kstep;
;             const char* a3 = a2 + kstep; const char* b3 = b2 + kstep;
.LBB0_487:
	v_mov_b32_e32 v123, 0
	s_andn2_b64 vcc, exec, s[14:15]
	v_mov_b32_e32 v122, v123
	v_mov_b32_e32 v121, v123
	v_mov_b32_e32 v120, v123
	v_mov_b32_e32 v127, v123
	v_mov_b32_e32 v126, v123
	v_mov_b32_e32 v125, v123
	v_mov_b32_e32 v124, v123
	v_mov_b32_e32 v111, v123
	v_mov_b32_e32 v110, v123
	v_mov_b32_e32 v109, v123
	v_mov_b32_e32 v108, v123
	v_mov_b32_e32 v107, v123
	v_mov_b32_e32 v106, v123
	v_mov_b32_e32 v105, v123
	v_mov_b32_e32 v104, v123
	v_mov_b32_e32 v95, v123
	v_mov_b32_e32 v94, v123
	v_mov_b32_e32 v93, v123
	v_mov_b32_e32 v92, v123
	v_mov_b32_e32 v91, v123
	v_mov_b32_e32 v90, v123
	v_mov_b32_e32 v89, v123
	v_mov_b32_e32 v88, v123
	v_mov_b32_e32 v79, v123
	v_mov_b32_e32 v78, v123
	v_mov_b32_e32 v77, v123
	v_mov_b32_e32 v76, v123
	v_mov_b32_e32 v75, v123
	v_mov_b32_e32 v74, v123
	v_mov_b32_e32 v73, v123
	v_mov_b32_e32 v72, v123
	v_mov_b32_e32 v119, v123
	v_mov_b32_e32 v118, v123
	v_mov_b32_e32 v117, v123
	v_mov_b32_e32 v116, v123
	v_mov_b32_e32 v115, v123
	v_mov_b32_e32 v114, v123
	v_mov_b32_e32 v113, v123
	v_mov_b32_e32 v112, v123
	v_mov_b32_e32 v103, v123
	v_mov_b32_e32 v102, v123
	v_mov_b32_e32 v101, v123
	v_mov_b32_e32 v100, v123
	v_mov_b32_e32 v99, v123
	v_mov_b32_e32 v98, v123
	v_mov_b32_e32 v97, v123
	v_mov_b32_e32 v96, v123
	v_mov_b32_e32 v87, v123
	v_mov_b32_e32 v86, v123
	v_mov_b32_e32 v85, v123
	v_mov_b32_e32 v84, v123
	v_mov_b32_e32 v83, v123
	v_mov_b32_e32 v82, v123
	v_mov_b32_e32 v81, v123
	v_mov_b32_e32 v80, v123
	v_mov_b32_e32 v71, v123
	v_mov_b32_e32 v70, v123
	v_mov_b32_e32 v69, v123
	v_mov_b32_e32 v68, v123
	v_mov_b32_e32 v67, v123
	v_mov_b32_e32 v66, v123
	v_mov_b32_e32 v65, v123
	v_mov_b32_e32 v64, v123
	v_mov_b32_e32 v63, v123
	v_mov_b32_e32 v62, v123
	v_mov_b32_e32 v61, v123
	v_mov_b32_e32 v60, v123
	v_mov_b32_e32 v59, v123
	v_mov_b32_e32 v58, v123
	v_mov_b32_e32 v57, v123
	v_mov_b32_e32 v56, v123
	v_mov_b32_e32 v47, v123
	v_mov_b32_e32 v46, v123
	v_mov_b32_e32 v45, v123
	v_mov_b32_e32 v44, v123
	v_mov_b32_e32 v43, v123
	v_mov_b32_e32 v42, v123
	v_mov_b32_e32 v41, v123
	v_mov_b32_e32 v40, v123
	v_mov_b32_e32 v31, v123
	v_mov_b32_e32 v30, v123
	v_mov_b32_e32 v29, v123
	v_mov_b32_e32 v28, v123
	v_mov_b32_e32 v27, v123
	v_mov_b32_e32 v26, v123
	v_mov_b32_e32 v25, v123
	v_mov_b32_e32 v24, v123
	v_mov_b32_e32 v15, v123
	v_mov_b32_e32 v14, v123
	v_mov_b32_e32 v13, v123
	v_mov_b32_e32 v12, v123
	v_mov_b32_e32 v11, v123
	v_mov_b32_e32 v10, v123
	v_mov_b32_e32 v9, v123
	v_mov_b32_e32 v8, v123
	v_mov_b32_e32 v55, v123
	v_mov_b32_e32 v54, v123
	v_mov_b32_e32 v53, v123
	v_mov_b32_e32 v52, v123
	v_mov_b32_e32 v51, v123
	v_mov_b32_e32 v50, v123
	v_mov_b32_e32 v49, v123
	v_mov_b32_e32 v48, v123
	v_mov_b32_e32 v39, v123
	v_mov_b32_e32 v38, v123
	v_mov_b32_e32 v37, v123
	v_mov_b32_e32 v36, v123
	v_mov_b32_e32 v35, v123
	v_mov_b32_e32 v34, v123
	v_mov_b32_e32 v33, v123
	v_mov_b32_e32 v32, v123
	v_mov_b32_e32 v23, v123
	v_mov_b32_e32 v22, v123
	v_mov_b32_e32 v21, v123
	v_mov_b32_e32 v20, v123
	v_mov_b32_e32 v19, v123
	v_mov_b32_e32 v18, v123
	v_mov_b32_e32 v17, v123
	v_mov_b32_e32 v16, v123
	v_mov_b32_e32 v7, v123
	v_mov_b32_e32 v6, v123
	v_mov_b32_e32 v5, v123
	v_mov_b32_e32 v4, v123
	v_mov_b32_e32 v3, v123
	v_mov_b32_e32 v2, v123
	v_mov_b32_e32 v1, v123
	v_mov_b32_e32 v0, v123
	s_cbranch_vccnz .LBB0_491
	s_add_u32 s20, s20, 0x80
	s_addc_u32 s21, s21, 0
	s_add_u32 s49, s22, 0x100
	v_mov_b32_e32 v0, 0
	s_addc_u32 s50, s23, 0
	s_mov_b32 s22, 0
	v_mov_b32_e32 v1, v0
	v_mov_b32_e32 v2, v0
	v_mov_b32_e32 v3, v0
	v_mov_b32_e32 v4, v0
	v_mov_b32_e32 v5, v0
	v_mov_b32_e32 v6, v0
	v_mov_b32_e32 v7, v0
	v_mov_b32_e32 v16, v0
	v_mov_b32_e32 v17, v0
	v_mov_b32_e32 v18, v0
	v_mov_b32_e32 v19, v0
	v_mov_b32_e32 v20, v0
	v_mov_b32_e32 v21, v0
	v_mov_b32_e32 v22, v0
	v_mov_b32_e32 v23, v0
	v_mov_b32_e32 v32, v0
	v_mov_b32_e32 v33, v0
	v_mov_b32_e32 v34, v0
	v_mov_b32_e32 v35, v0
	v_mov_b32_e32 v36, v0
	v_mov_b32_e32 v37, v0
	v_mov_b32_e32 v38, v0
	v_mov_b32_e32 v39, v0
	v_mov_b32_e32 v48, v0
	v_mov_b32_e32 v49, v0
	v_mov_b32_e32 v50, v0
	v_mov_b32_e32 v51, v0
	v_mov_b32_e32 v52, v0
	v_mov_b32_e32 v53, v0
	v_mov_b32_e32 v54, v0
	v_mov_b32_e32 v55, v0
	v_mov_b32_e32 v8, v0
	v_mov_b32_e32 v9, v0
	v_mov_b32_e32 v10, v0
	v_mov_b32_e32 v11, v0
	v_mov_b32_e32 v12, v0
	v_mov_b32_e32 v13, v0
	v_mov_b32_e32 v14, v0
	v_mov_b32_e32 v15, v0
	v_mov_b32_e32 v24, v0
	v_mov_b32_e32 v25, v0
	v_mov_b32_e32 v26, v0
	v_mov_b32_e32 v27, v0
	v_mov_b32_e32 v28, v0
	v_mov_b32_e32 v29, v0
	v_mov_b32_e32 v30, v0
	v_mov_b32_e32 v31, v0
	v_mov_b32_e32 v40, v0
	v_mov_b32_e32 v41, v0
	v_mov_b32_e32 v42, v0
	v_mov_b32_e32 v43, v0
	v_mov_b32_e32 v44, v0
	v_mov_b32_e32 v45, v0
	v_mov_b32_e32 v46, v0
	v_mov_b32_e32 v47, v0
	v_mov_b32_e32 v56, v0
	v_mov_b32_e32 v57, v0
	v_mov_b32_e32 v58, v0
	v_mov_b32_e32 v59, v0
	v_mov_b32_e32 v60, v0
	v_mov_b32_e32 v61, v0
	v_mov_b32_e32 v62, v0
	v_mov_b32_e32 v63, v0
	v_mov_b32_e32 v64, v0
	v_mov_b32_e32 v65, v0
	v_mov_b32_e32 v66, v0
	v_mov_b32_e32 v67, v0
	v_mov_b32_e32 v68, v0
	v_mov_b32_e32 v69, v0
	v_mov_b32_e32 v70, v0
	v_mov_b32_e32 v71, v0
	v_mov_b32_e32 v80, v0
	v_mov_b32_e32 v81, v0
	v_mov_b32_e32 v82, v0
	v_mov_b32_e32 v83, v0
	v_mov_b32_e32 v84, v0
	v_mov_b32_e32 v85, v0
	v_mov_b32_e32 v86, v0
	v_mov_b32_e32 v87, v0
	v_mov_b32_e32 v96, v0
	v_mov_b32_e32 v97, v0
	v_mov_b32_e32 v98, v0
	v_mov_b32_e32 v99, v0
	v_mov_b32_e32 v100, v0
	v_mov_b32_e32 v101, v0
	v_mov_b32_e32 v102, v0
	v_mov_b32_e32 v103, v0
	v_mov_b32_e32 v112, v0
	v_mov_b32_e32 v113, v0
	v_mov_b32_e32 v114, v0
	v_mov_b32_e32 v115, v0
	v_mov_b32_e32 v116, v0
	v_mov_b32_e32 v117, v0
	v_mov_b32_e32 v118, v0
	v_mov_b32_e32 v119, v0
	v_mov_b32_e32 v72, v0
	v_mov_b32_e32 v73, v0
	v_mov_b32_e32 v74, v0
	v_mov_b32_e32 v75, v0
	v_mov_b32_e32 v76, v0
	v_mov_b32_e32 v77, v0
	v_mov_b32_e32 v78, v0
	v_mov_b32_e32 v79, v0
	v_mov_b32_e32 v88, v0
	v_mov_b32_e32 v89, v0
	v_mov_b32_e32 v90, v0
	v_mov_b32_e32 v91, v0
	v_mov_b32_e32 v92, v0
	v_mov_b32_e32 v93, v0
	v_mov_b32_e32 v94, v0
	v_mov_b32_e32 v95, v0
	v_mov_b32_e32 v104, v0
	v_mov_b32_e32 v105, v0
	v_mov_b32_e32 v106, v0
	v_mov_b32_e32 v107, v0
	v_mov_b32_e32 v108, v0
	v_mov_b32_e32 v109, v0
	v_mov_b32_e32 v110, v0
	v_mov_b32_e32 v111, v0
	v_mov_b32_e32 v124, v0
	v_mov_b32_e32 v125, v0
	v_mov_b32_e32 v126, v0
	v_mov_b32_e32 v127, v0
	v_mov_b32_e32 v120, v0
	v_mov_b32_e32 v121, v0
	v_mov_b32_e32 v122, v0
	v_mov_b32_e32 v123, v0
	.p2align	6

; #define ATT_LOAD(S, j) do { rk##S = *(const u32x4*)(ksrc + (size_t)(j) * 64 * 1024); if (!DIFF && tid < 256) rk2##S = *(const u32x4*)(k2src + (size_t)(j) * 64 * 32); \
;         rv0##S = *(const u32x4*)(vsrc + (size_t)(j) * 64 * 1024); if (DIFF) rv1##S = *(const u32x4*)(vsrc + (size_t)(j) * 64 * 1024 + 32 * 1024); } while (0)
; #define ATT_STORE(S, bufp) do { *(LAS u32x4*)((bufp) + kdst) = rk##S; if (!DIFF && tid < 256) *(LAS u32x4*)((bufp) + k2dst) = rk2##S; \
;         *(LAS u32x4*)((bufp) + vdst) = rv0##S; if (DIFF) *(LAS u32x4*)((bufp) + vdst + 32 * PV) = rv1##S; } while (0)
; template <bool DIFF>
; __device__ __forceinline__ void attn_unit_coop(const Grp& G, int b, int h, int qb, int n, LAS unsigned char* lds, const int tid_in) {
;     ...
;         AttnState<DQK, DV> st; attn_init(st);
;         if (DIFF) { const bf16* qp = G.QD + (seq0 + qrow0 + q) * 1024 + h * 128 + n * 64 + hi * 8;
; #pragma unroll
;             for (int ks = 0; ks < 4; ++ks) st.qf[ks] = *(const bf16x8*)(qp + ks * 16);
;         } else { const bf16* qn = G.QN + (seq0 + qrow0 + q) * 1024 + h * 64 + hi * 8; const bf16* qr = G.QR + (seq0 + qrow0 + q) * 512 + h * 32 + hi * 8;
; #pragma unroll
;             for (int ks = 0; ks < 4; ++ks) st.qf[ks] = *(const bf16x8*)(qn + ks * 16);
; #pragma unroll
;             for (int ks = 0; ks < 2; ++ks) st.qf[4 + ks] = *(const bf16x8*)(qr + ks * 16);
;         }
;         const bf16* ksrc = (DIFF ? G.KD + h * 128 + n * 64 : G.KN + h * 64) + (seq0 + (tid >> 3)) * 1024 + (tid & 7) * 8;
;         const int kdst = (tid >> 3) * PK + (tid & 7) * 16;
;         const bf16* k2src = G.KR + (seq0 + ((tid & 255) >> 2)) * 32 + (tid & 3) * 8;
;         const int k2dst = ((tid & 255) >> 2) * PK + 128 + (tid & 3) * 16;
;         const bf16* vsrc = DIFF ? G.VD + (seq0 + (tid >> 4)) * 1024 + h * 128 + (tid & 15) * 8 : G.VM + (seq0 + (tid >> 3)) * 1024 + h * 64 + (tid & 7) * 8;
;         const int vdst = DIFF ? KB + (tid >> 4) * PV + (tid & 15) * 16 : KB + (tid >> 3) * PV + (tid & 7) * 16;
;         u32x4 rkA, rk2A = {0u, 0u, 0u, 0u}, rv0A, rv1A = {0u, 0u, 0u, 0u}, rkB = {0u, 0u, 0u, 0u}, rk2B = {0u, 0u, 0u, 0u}, rv0B = {0u, 0u, 0u, 0u}, rv1B = {0u, 0u, 0u, 0u};
;     ...
;         ATT_LOAD(A, 0); ATT_STORE(A, tiles);
;         __syncthreads();
;         ATT_LOAD(A, 1);
;         for (int j = 0; j < NT; j += 2) {
.LBB0_519:
	v_mov_b32_e32 v28, v212
	v_mov_b32_e32 v15, v185
	v_ashrrev_i32_e32 v12, 3, v28
	v_ashrrev_i32_e32 v13, 31, v12
	v_lshl_add_u64 v[0:1], s[24:25], 0, v[12:13]
	v_lshlrev_b64 v[0:1], 11, v[0:1]
	v_lshlrev_b32_e32 v2, 4, v28
	v_ashrrev_i32_e32 v18, 4, v28
	v_lshl_add_u64 v[0:1], s[30:31], 0, v[0:1]
	v_and_b32_e32 v14, 0x70, v2
	v_ashrrev_i32_e32 v19, 31, v18
	v_lshl_add_u64 v[16:17], v[0:1], 0, v[14:15]
	v_lshl_add_u64 v[0:1], s[24:25], 0, v[18:19]
	v_lshlrev_b64 v[0:1], 11, v[0:1]
	v_lshl_add_u64 v[0:1], s[14:15], 0, v[0:1]
	v_and_b32_e32 v20, 0xf0, v2
	v_mov_b32_e32 v21, v185
	v_lshl_add_u64 v[22:23], v[0:1], 0, v[20:21]
	global_load_dwordx4 v[0:3], v[16:17], off
	global_load_dwordx4 v[4:7], v[22:23], off
	v_add_co_u32_e32 v8, vcc, s53, v22
	s_xor_b64 s[36:37], s[0:1], -1
	s_nop 0
	v_addc_co_u32_e32 v9, vcc, 0, v23, vcc
	global_load_dwordx4 v[8:11], v[8:9], off
	s_and_b64 s[0:1], s[0:1], exec
	s_cselect_b32 s0, s48, s90
	v_readfirstlane_b32 s1, v28
	s_lshl_b32 s2, s0, 8
	s_ashr_i32 s3, s1, 1
	s_lshl_b32 s7, s0, 2
	s_ashr_i32 s40, s1, 7
	s_and_b32 s41, s1, 0x3fffffc0
	v_mad_u64_u32 v[24:25], s[0:1], v12, s76, v[14:15]
	s_andn2_b32 s3, s3, 31
	s_movk_i32 s0, 0x140
	v_mad_u64_u32 v[26:27], s[0:1], v18, s0, v[20:21]
	s_add_i32 s42, s3, s2
	s_ashr_i32 s0, s42, 31
	s_add_u32 s38, s24, s42
	v_and_b32_e32 v194, 31, v28
	s_addc_u32 s39, s25, s0
	v_add_u32_e32 v214, 0, v24
	v_or_b32_e32 v24, s38, v194
	v_add_co_u32_e32 v16, vcc, s62, v16
	v_mov_b32_e32 v25, s39
	v_bfe_u32 v191, v28, 5, 1
	v_addc_co_u32_e32 v17, vcc, 0, v17, vcc
	v_lshlrev_b64 v[24:25], 11, v[24:25]
	v_lshlrev_b32_e32 v184, 4, v191
	v_add_u32_e32 v215, 0, v26
	v_add_co_u32_e32 v26, vcc, s62, v22
	v_lshl_add_u64 v[24:25], s[28:29], 0, v[24:25]
	s_nop 0
	v_addc_co_u32_e32 v27, vcc, 0, v23, vcc
	s_mov_b32 s0, 0x30000
	v_lshl_add_u64 v[24:25], v[24:25], 0, v[184:185]
	v_add_co_u32_e32 v22, vcc, s0, v22
	global_load_dwordx4 v[112:115], v[24:25], off
	global_load_dwordx4 v[116:119], v[24:25], off offset:32
	global_load_dwordx4 v[120:123], v[24:25], off offset:64
	global_load_dwordx4 v[124:127], v[24:25], off offset:96
	v_addc_co_u32_e32 v23, vcc, 0, v23, vcc
	s_lshl_b32 s0, s41, 2
	s_add_i32 s6, s7, 4
	s_add_i32 s7, s40, s7
	s_add_i32 s40, s0, 0
	v_mov_b32_e32 v142, v185
	v_mov_b32_e32 v143, v185
	v_mov_b32_e32 v48, v185
	v_mov_b32_e32 v49, v185
	v_mov_b32_e32 v62, v185
	v_mov_b32_e32 v63, v185
	v_mov_b32_e32 v140, v185
	v_mov_b32_e32 v141, v185
	v_mov_b32_e32 v50, v185
	v_mov_b32_e32 v51, v185
	v_mov_b32_e32 v52, v185
	v_mov_b32_e32 v53, v185
	v_mov_b32_e32 v54, v185
	v_mov_b32_e32 v55, v185
	v_mov_b32_e32 v56, v185
	v_mov_b32_e32 v57, v185
	v_mov_b32_e32 v58, v185
	v_mov_b32_e32 v59, v185
	s_waitcnt vmcnt(6)
	ds_write_b128 v214, v[0:3] offset:8192
	s_waitcnt vmcnt(5)
	ds_write_b128 v215, v[4:7] offset:17408
	s_waitcnt vmcnt(4)
	ds_write_b128 v215, v[8:11] offset:27648
	s_waitcnt lgkmcnt(0)
	s_barrier
	global_load_dwordx4 v[128:131], v[16:17], off
	global_load_dwordx4 v[132:135], v[26:27], off
	global_load_dwordx4 v[136:139], v[22:23], off
	v_and_b32_e32 v0, 63, v28
	v_lshlrev_b32_e32 v1, 2, v191
	v_lshrrev_b32_e32 v3, 2, v28
	v_and_b32_e32 v4, 16, v28
	v_lshlrev_b32_e32 v5, 2, v28
	v_and_or_b32 v4, v5, 12, v4
	v_cmp_gt_u32_e64 s[0:1], 32, v0
	v_and_or_b32 v0, v3, 3, v1
	v_lshlrev_b32_e32 v4, 1, v4
	v_mul_u32_u24_e32 v0, 0x140, v0
	v_add3_u32 v217, 0, v4, v0
	v_or_b32_e32 v0, s42, v194
	v_sub_u32_e32 v218, v1, v0
	v_sub_u32_e32 v0, v1, v194
	v_subrev_u32_e32 v0, s3, v0
	v_subrev_u32_e32 v219, s2, v0
	s_mul_i32 s98, s85, 5
	s_add_i32 s98, s98, 0x11380
	v_lshl_add_u32 v225, v218, 2, s98
	v_lshlrev_b64 v[0:1], 11, v[18:19]
	v_or_b32_e32 v0, v0, v20
	v_lshl_add_u64 v[196:197], s[22:23], 0, v[0:1]
	v_lshlrev_b64 v[0:1], 11, v[12:13]
	v_mad_u32_u24 v2, v194, s76, 0
	v_or_b32_e32 v0, v0, v14
	v_lshl_add_u64 v[198:199], s[34:35], 0, v[0:1]
	v_mov_b32_e32 v60, v185
	v_mov_b32_e32 v61, v185
	v_add_u32_e32 v221, v2, v184
	v_mov_b64_e32 v[32:33], v[48:49]
	v_mov_b64_e32 v[16:17], v[48:49]
	v_mov_b64_e32 v[0:1], v[48:49]
	v_mov_b64_e32 v[78:79], v[62:63]
	v_mov_b64_e32 v[146:147], v[142:143]
	v_mov_b64_e32 v[150:151], v[142:143]
	s_mov_b32 s58, 0
	v_lshl_add_u32 v216, v194, 2, s40
	v_add_u32_e32 v213, s40, v184
	s_sub_i32 s92, 0, s42
	v_mov_b32_e32 v220, 0
	v_mov_b64_e32 v[34:35], v[50:51]
	v_mov_b64_e32 v[36:37], v[52:53]
	v_mov_b64_e32 v[38:39], v[54:55]
	v_mov_b64_e32 v[40:41], v[56:57]
	v_mov_b64_e32 v[42:43], v[58:59]
	v_mov_b64_e32 v[44:45], v[60:61]
	v_mov_b64_e32 v[46:47], v[62:63]
	v_mov_b64_e32 v[18:19], v[50:51]
	v_mov_b64_e32 v[20:21], v[52:53]
	v_mov_b64_e32 v[22:23], v[54:55]
	v_mov_b64_e32 v[24:25], v[56:57]
	v_mov_b64_e32 v[26:27], v[58:59]
	v_mov_b64_e32 v[28:29], v[60:61]
	v_mov_b64_e32 v[30:31], v[62:63]
	v_mov_b64_e32 v[2:3], v[50:51]
	v_mov_b64_e32 v[4:5], v[52:53]
	v_mov_b64_e32 v[6:7], v[54:55]
	v_mov_b64_e32 v[8:9], v[56:57]
	v_mov_b64_e32 v[10:11], v[58:59]
	v_mov_b64_e32 v[12:13], v[60:61]
	v_mov_b64_e32 v[14:15], v[62:63]
	v_mov_b64_e32 v[76:77], v[60:61]
	v_mov_b64_e32 v[74:75], v[58:59]
	v_mov_b64_e32 v[72:73], v[56:57]
	v_mov_b64_e32 v[70:71], v[54:55]
	v_mov_b64_e32 v[68:69], v[52:53]
	v_mov_b64_e32 v[66:67], v[50:51]
	v_mov_b64_e32 v[64:65], v[48:49]
	v_mov_b32_e32 v184, 0
	v_mov_b64_e32 v[144:145], v[140:141]
	v_mov_b64_e32 v[148:149], v[140:141]
	s_mov_b32 s59, 0
	.p2align	6

; #define ATT_LOAD(S, j) do { rk##S = *(const u32x4*)(ksrc + (size_t)(j) * 64 * 1024); if (!DIFF && tid < 256) rk2##S = *(const u32x4*)(k2src + (size_t)(j) * 64 * 32); \
;         rv0##S = *(const u32x4*)(vsrc + (size_t)(j) * 64 * 1024); if (DIFF) rv1##S = *(const u32x4*)(vsrc + (size_t)(j) * 64 * 1024 + 32 * 1024); } while (0)
; #define ATT_STORE(S, bufp) do { *(LAS u32x4*)((bufp) + kdst) = rk##S; if (!DIFF && tid < 256) *(LAS u32x4*)((bufp) + k2dst) = rk2##S; \
;         *(LAS u32x4*)((bufp) + vdst) = rv0##S; if (DIFF) *(LAS u32x4*)((bufp) + vdst + 32 * PV) = rv1##S; } while (0)
; template <bool DIFF>
; __device__ __forceinline__ void attn_unit_coop(const Grp& G, int b, int h, int qb, int n, LAS unsigned char* lds, const int tid_in) {
;     ...
;         } else { const bf16* qn = G.QN + (seq0 + qrow0 + q) * 1024 + h * 64 + hi * 8; const bf16* qr = G.QR + (seq0 + qrow0 + q) * 512 + h * 32 + hi * 8;
; #pragma unroll
;             for (int ks = 0; ks < 4; ++ks) st.qf[ks] = *(const bf16x8*)(qn + ks * 16);
; #pragma unroll
;             for (int ks = 0; ks < 2; ++ks) st.qf[4 + ks] = *(const bf16x8*)(qr + ks * 16);
;         }
;         const bf16* ksrc = (DIFF ? G.KD + h * 128 + n * 64 : G.KN + h * 64) + (seq0 + (tid >> 3)) * 1024 + (tid & 7) * 8;
;         const int kdst = (tid >> 3) * PK + (tid & 7) * 16;
;         const bf16* k2src = G.KR + (seq0 + ((tid & 255) >> 2)) * 32 + (tid & 3) * 8;
;         const int k2dst = ((tid & 255) >> 2) * PK + 128 + (tid & 3) * 16;
;         const bf16* vsrc = DIFF ? G.VD + (seq0 + (tid >> 4)) * 1024 + h * 128 + (tid & 15) * 8 : G.VM + (seq0 + (tid >> 3)) * 1024 + h * 64 + (tid & 7) * 8;
;         const int vdst = DIFF ? KB + (tid >> 4) * PV + (tid & 15) * 16 : KB + (tid >> 3) * PV + (tid & 7) * 16;
;         u32x4 rkA, rk2A = {0u, 0u, 0u, 0u}, rv0A, rv1A = {0u, 0u, 0u, 0u}, rkB = {0u, 0u, 0u, 0u}, rk2B = {0u, 0u, 0u, 0u}, rv0B = {0u, 0u, 0u, 0u}, rv1B = {0u, 0u, 0u, 0u};
;     ...
;         ATT_LOAD(A, 0); ATT_STORE(A, tiles);
;         __syncthreads();
;         ATT_LOAD(A, 1);
;         for (int j = 0; j < NT; j += 2) {
.LBB0_569:
	s_or_b64 exec, exec, s[4:5]
	v_add_co_u32_e32 v0, vcc, 0x20000, v16
	s_xor_b64 s[28:29], s[2:3], -1
	s_nop 0
	v_addc_co_u32_e32 v1, vcc, 0, v17, vcc
	global_load_dwordx4 v[112:115], v[0:1], off
	v_bfe_u32 v1, v18, 2, 2
	v_and_b32_e32 v0, 63, v18
	v_lshl_or_b32 v1, v153, 2, v1
	s_lshl_b32 s2, s6, 2
	s_ashr_i32 s6, s7, 7
	s_and_b32 s3, s7, 0x3fffffc0
	v_and_b32_e32 v3, 16, v18
	v_mad_u32_u24 v4, v1, s52, 0
	v_lshlrev_b32_e32 v1, 2, v0
	s_add_i32 s6, s6, s2
	s_add_i32 s7, s2, 4
	s_lshl_b32 s2, s3, 2
	v_and_or_b32 v1, v1, 12, v3
	s_add_i32 s4, s2, 0
	v_lshlrev_b32_e32 v3, 1, v1
	v_cmp_gt_u32_e64 s[2:3], 32, v0
	v_lshl_or_b32 v0, v20, 6, v10
	v_mov_b32_e32 v1, v185
	v_lshl_add_u64 v[144:145], s[22:23], 0, v[0:1]
	v_lshlrev_b64 v[0:1], 11, v[8:9]
	v_mad_u32_u24 v2, v154, s78, 0
	v_lshl_or_b32 v0, v19, 4, v0
	v_mov_b32_e32 v118, v185
	v_mov_b32_e32 v119, v185
	v_mov_b32_e32 v16, v185
	v_mov_b32_e32 v17, v185
	v_mov_b32_e32 v30, v185
	v_mov_b32_e32 v31, v185
	v_add_u32_e32 v159, v10, v11
	v_lshl_add_u64 v[146:147], s[24:25], 0, v[0:1]
	v_lshl_add_u64 v[148:149], s[26:27], 0, v[0:1]
	v_mov_b32_e32 v116, v185
	v_mov_b32_e32 v117, v185
	v_mov_b32_e32 v18, v185
	v_mov_b32_e32 v19, v185
	v_mov_b32_e32 v20, v185
	v_mov_b32_e32 v21, v185
	v_mov_b32_e32 v22, v185
	v_mov_b32_e32 v23, v185
	v_mov_b32_e32 v24, v185
	v_mov_b32_e32 v25, v185
	v_mov_b32_e32 v26, v185
	v_mov_b32_e32 v27, v185
	v_mov_b32_e32 v28, v185
	v_mov_b32_e32 v29, v185
	v_add_u32_e32 v162, v2, v184
	v_add_u32_e32 v163, v4, v3
	v_mov_b64_e32 v[0:1], v[16:17]
	v_mov_b64_e32 v[46:47], v[30:31]
	v_mov_b64_e32 v[122:123], v[118:119]
	v_mov_b64_e32 v[126:127], v[118:119]
	s_mov_b32 s58, 0
	v_lshl_add_u32 v158, v154, 2, s4
	v_add_u32_e32 v155, s4, v184
	v_mov_b32_e32 v161, 0
	v_mov_b64_e32 v[2:3], v[18:19]
	v_mov_b64_e32 v[4:5], v[20:21]
	v_mov_b64_e32 v[6:7], v[22:23]
	v_mov_b64_e32 v[8:9], v[24:25]
	v_mov_b64_e32 v[10:11], v[26:27]
	v_mov_b64_e32 v[12:13], v[28:29]
	v_mov_b64_e32 v[14:15], v[30:31]
	v_mov_b64_e32 v[44:45], v[28:29]
	v_mov_b64_e32 v[42:43], v[26:27]
	v_mov_b64_e32 v[40:41], v[24:25]
	v_mov_b64_e32 v[38:39], v[22:23]
	v_mov_b64_e32 v[36:37], v[20:21]
	v_mov_b64_e32 v[34:35], v[18:19]
	v_mov_b64_e32 v[32:33], v[16:17]
	v_mov_b32_e32 v160, 0
	v_mov_b64_e32 v[120:121], v[116:117]
	v_mov_b64_e32 v[124:125], v[116:117]
	.p2align	6

; template <class Epi, class Sched, bool ALIGN_EPI = false, bool SP2 = false>
; __device__ __forceinline__ void gemm_phase(PG8_LAS unsigned char* lds, const Gemm g, const Sched& S, const Epi& E, const int tid_in) {
;     ...
;     f32x4 acc[2][2][4][2];
; #pragma unroll
;     for (int a = 0; a < 2; ++a)
; #pragma unroll
;         for (int b = 0; b < 2; ++b)
; #pragma unroll
;             for (int m = 0; m < 4; ++m)
; #pragma unroll
;                 for (int n = 0; n < 2; ++n) acc[a][b][m][n] = (f32x4){0.f, 0.f, 0.f, 0.f};
;     ...
;     for (;;) {
;         const bool has_next = S.next(ui + 1, nxt);
;         const char* nA = has_next ? (const char*)g.A + (size_t)nxt.pm * tstep : cA; const char* nB = has_next ? (const char*)g.Bt + (size_t)nxt.pn * tstep : cB;
;         for (int t = 0; t < nt; t += 2) {
;             const bool last = (t == nt - 2);
;             const char* a1 = cA + (size_t)(t + 1) * kstep;
;             const char* a2 = last ? nA : cA + (size_t)(t + 2) * kstep; const char* b2 = last ? nB : cB + (size_t)(t + 2) * kstep;
;             const char* a3 = a2 + kstep; const char* b3 = b2 + kstep;
.LBB0_680:
	v_mov_b32_e32 v127, 0
	s_andn2_b64 vcc, exec, s[18:19]
	v_mov_b32_e32 v126, v127
	v_mov_b32_e32 v125, v127
	v_mov_b32_e32 v124, v127
	v_mov_b32_e32 v123, v127
	v_mov_b32_e32 v122, v127
	v_mov_b32_e32 v121, v127
	v_mov_b32_e32 v120, v127
	v_mov_b32_e32 v111, v127
	v_mov_b32_e32 v110, v127
	v_mov_b32_e32 v109, v127
	v_mov_b32_e32 v108, v127
	v_mov_b32_e32 v107, v127
	v_mov_b32_e32 v106, v127
	v_mov_b32_e32 v105, v127
	v_mov_b32_e32 v104, v127
	v_mov_b32_e32 v95, v127
	v_mov_b32_e32 v94, v127
	v_mov_b32_e32 v93, v127
	v_mov_b32_e32 v92, v127
	v_mov_b32_e32 v91, v127
	v_mov_b32_e32 v90, v127
	v_mov_b32_e32 v89, v127
	v_mov_b32_e32 v88, v127
	v_mov_b32_e32 v79, v127
	v_mov_b32_e32 v78, v127
	v_mov_b32_e32 v77, v127
	v_mov_b32_e32 v76, v127
	v_mov_b32_e32 v75, v127
	v_mov_b32_e32 v74, v127
	v_mov_b32_e32 v73, v127
	v_mov_b32_e32 v72, v127
	v_mov_b32_e32 v119, v127
	v_mov_b32_e32 v118, v127
	v_mov_b32_e32 v117, v127
	v_mov_b32_e32 v116, v127
	v_mov_b32_e32 v115, v127
	v_mov_b32_e32 v114, v127
	v_mov_b32_e32 v113, v127
	v_mov_b32_e32 v112, v127
	v_mov_b32_e32 v103, v127
	v_mov_b32_e32 v102, v127
	v_mov_b32_e32 v101, v127
	v_mov_b32_e32 v100, v127
	v_mov_b32_e32 v99, v127
	v_mov_b32_e32 v98, v127
	v_mov_b32_e32 v97, v127
	v_mov_b32_e32 v96, v127
	v_mov_b32_e32 v87, v127
	v_mov_b32_e32 v86, v127
	v_mov_b32_e32 v85, v127
	v_mov_b32_e32 v84, v127
	v_mov_b32_e32 v83, v127
	v_mov_b32_e32 v82, v127
	v_mov_b32_e32 v81, v127
	v_mov_b32_e32 v80, v127
	v_mov_b32_e32 v71, v127
	v_mov_b32_e32 v70, v127
	v_mov_b32_e32 v69, v127
	v_mov_b32_e32 v68, v127
	v_mov_b32_e32 v67, v127
	v_mov_b32_e32 v66, v127
	v_mov_b32_e32 v65, v127
	v_mov_b32_e32 v64, v127
	v_mov_b32_e32 v63, v127
	v_mov_b32_e32 v62, v127
	v_mov_b32_e32 v61, v127
	v_mov_b32_e32 v60, v127
	v_mov_b32_e32 v59, v127
	v_mov_b32_e32 v58, v127
	v_mov_b32_e32 v57, v127
	v_mov_b32_e32 v56, v127
	v_mov_b32_e32 v47, v127
	v_mov_b32_e32 v46, v127
	v_mov_b32_e32 v45, v127
	v_mov_b32_e32 v44, v127
	v_mov_b32_e32 v43, v127
	v_mov_b32_e32 v42, v127
	v_mov_b32_e32 v41, v127
	v_mov_b32_e32 v40, v127
	v_mov_b32_e32 v31, v127
	v_mov_b32_e32 v30, v127
	v_mov_b32_e32 v29, v127
	v_mov_b32_e32 v28, v127
	v_mov_b32_e32 v27, v127
	v_mov_b32_e32 v26, v127
	v_mov_b32_e32 v25, v127
	v_mov_b32_e32 v24, v127
	v_mov_b32_e32 v15, v127
	v_mov_b32_e32 v14, v127
	v_mov_b32_e32 v13, v127
	v_mov_b32_e32 v12, v127
	v_mov_b32_e32 v11, v127
	v_mov_b32_e32 v10, v127
	v_mov_b32_e32 v9, v127
	v_mov_b32_e32 v8, v127
	v_mov_b32_e32 v55, v127
	v_mov_b32_e32 v54, v127
	v_mov_b32_e32 v53, v127
	v_mov_b32_e32 v52, v127
	v_mov_b32_e32 v51, v127
	v_mov_b32_e32 v50, v127
	v_mov_b32_e32 v49, v127
	v_mov_b32_e32 v48, v127
	v_mov_b32_e32 v39, v127
	v_mov_b32_e32 v38, v127
	v_mov_b32_e32 v37, v127
	v_mov_b32_e32 v36, v127
	v_mov_b32_e32 v35, v127
	v_mov_b32_e32 v34, v127
	v_mov_b32_e32 v33, v127
	v_mov_b32_e32 v32, v127
	v_mov_b32_e32 v23, v127
	v_mov_b32_e32 v22, v127
	v_mov_b32_e32 v21, v127
	v_mov_b32_e32 v20, v127
	v_mov_b32_e32 v19, v127
	v_mov_b32_e32 v18, v127
	v_mov_b32_e32 v17, v127
	v_mov_b32_e32 v16, v127
	v_mov_b32_e32 v7, v127
	v_mov_b32_e32 v6, v127
	v_mov_b32_e32 v5, v127
	v_mov_b32_e32 v4, v127
	v_mov_b32_e32 v3, v127
	v_mov_b32_e32 v2, v127
	v_mov_b32_e32 v1, v127
	v_mov_b32_e32 v0, v127
	s_cbranch_vccnz .LBB0_684
	s_add_u32 s22, s22, 0x80
	s_addc_u32 s23, s23, 0
	s_add_u32 s56, s28, 0x100
	v_mov_b32_e32 v0, 0
	s_addc_u32 s57, s29, 0
	s_mov_b32 s28, 0
	v_mov_b32_e32 v1, v0
	v_mov_b32_e32 v2, v0
	v_mov_b32_e32 v3, v0
	v_mov_b32_e32 v4, v0
	v_mov_b32_e32 v5, v0
	v_mov_b32_e32 v6, v0
	v_mov_b32_e32 v7, v0
	v_mov_b32_e32 v16, v0
	v_mov_b32_e32 v17, v0
	v_mov_b32_e32 v18, v0
	v_mov_b32_e32 v19, v0
	v_mov_b32_e32 v20, v0
	v_mov_b32_e32 v21, v0
	v_mov_b32_e32 v22, v0
	v_mov_b32_e32 v23, v0
	v_mov_b32_e32 v32, v0
	v_mov_b32_e32 v33, v0
	v_mov_b32_e32 v34, v0
	v_mov_b32_e32 v35, v0
	v_mov_b32_e32 v36, v0
	v_mov_b32_e32 v37, v0
	v_mov_b32_e32 v38, v0
	v_mov_b32_e32 v39, v0
	v_mov_b32_e32 v48, v0
	v_mov_b32_e32 v49, v0
	v_mov_b32_e32 v50, v0
	v_mov_b32_e32 v51, v0
	v_mov_b32_e32 v52, v0
	v_mov_b32_e32 v53, v0
	v_mov_b32_e32 v54, v0
	v_mov_b32_e32 v55, v0
	v_mov_b32_e32 v8, v0
	v_mov_b32_e32 v9, v0
	v_mov_b32_e32 v10, v0
	v_mov_b32_e32 v11, v0
	v_mov_b32_e32 v12, v0
	v_mov_b32_e32 v13, v0
	v_mov_b32_e32 v14, v0
	v_mov_b32_e32 v15, v0
	v_mov_b32_e32 v24, v0
	v_mov_b32_e32 v25, v0
	v_mov_b32_e32 v26, v0
	v_mov_b32_e32 v27, v0
	v_mov_b32_e32 v28, v0
	v_mov_b32_e32 v29, v0
	v_mov_b32_e32 v30, v0
	v_mov_b32_e32 v31, v0
	v_mov_b32_e32 v40, v0
	v_mov_b32_e32 v41, v0
	v_mov_b32_e32 v42, v0
	v_mov_b32_e32 v43, v0
	v_mov_b32_e32 v44, v0
	v_mov_b32_e32 v45, v0
	v_mov_b32_e32 v46, v0
	v_mov_b32_e32 v47, v0
	v_mov_b32_e32 v56, v0
	v_mov_b32_e32 v57, v0
	v_mov_b32_e32 v58, v0
	v_mov_b32_e32 v59, v0
	v_mov_b32_e32 v60, v0
	v_mov_b32_e32 v61, v0
	v_mov_b32_e32 v62, v0
	v_mov_b32_e32 v63, v0
	v_mov_b32_e32 v64, v0
	v_mov_b32_e32 v65, v0
	v_mov_b32_e32 v66, v0
	v_mov_b32_e32 v67, v0
	v_mov_b32_e32 v68, v0
	v_mov_b32_e32 v69, v0
	v_mov_b32_e32 v70, v0
	v_mov_b32_e32 v71, v0
	v_mov_b32_e32 v80, v0
	v_mov_b32_e32 v81, v0
	v_mov_b32_e32 v82, v0
	v_mov_b32_e32 v83, v0
	v_mov_b32_e32 v84, v0
	v_mov_b32_e32 v85, v0
	v_mov_b32_e32 v86, v0
	v_mov_b32_e32 v87, v0
	v_mov_b32_e32 v96, v0
	v_mov_b32_e32 v97, v0
	v_mov_b32_e32 v98, v0
	v_mov_b32_e32 v99, v0
	v_mov_b32_e32 v100, v0
	v_mov_b32_e32 v101, v0
	v_mov_b32_e32 v102, v0
	v_mov_b32_e32 v103, v0
	v_mov_b32_e32 v112, v0
	v_mov_b32_e32 v113, v0
	v_mov_b32_e32 v114, v0
	v_mov_b32_e32 v115, v0
	v_mov_b32_e32 v116, v0
	v_mov_b32_e32 v117, v0
	v_mov_b32_e32 v118, v0
	v_mov_b32_e32 v119, v0
	v_mov_b32_e32 v72, v0
	v_mov_b32_e32 v73, v0
	v_mov_b32_e32 v74, v0
	v_mov_b32_e32 v75, v0
	v_mov_b32_e32 v76, v0
	v_mov_b32_e32 v77, v0
	v_mov_b32_e32 v78, v0
	v_mov_b32_e32 v79, v0
	v_mov_b32_e32 v88, v0
	v_mov_b32_e32 v89, v0
	v_mov_b32_e32 v90, v0
	v_mov_b32_e32 v91, v0
	v_mov_b32_e32 v92, v0
	v_mov_b32_e32 v93, v0
	v_mov_b32_e32 v94, v0
	v_mov_b32_e32 v95, v0
	v_mov_b32_e32 v104, v0
	v_mov_b32_e32 v105, v0
	v_mov_b32_e32 v106, v0
	v_mov_b32_e32 v107, v0
	v_mov_b32_e32 v108, v0
	v_mov_b32_e32 v109, v0
	v_mov_b32_e32 v110, v0
	v_mov_b32_e32 v111, v0
	v_mov_b32_e32 v120, v0
	v_mov_b32_e32 v121, v0
	v_mov_b32_e32 v122, v0
	v_mov_b32_e32 v123, v0
	v_mov_b32_e32 v124, v0
	v_mov_b32_e32 v125, v0
	v_mov_b32_e32 v126, v0
	v_mov_b32_e32 v127, v0
	.p2align	6

; template <class Epi, class Sched, bool ALIGN_EPI = false, bool SP2 = false>
; __device__ __forceinline__ void gemm_phase(PG8_LAS unsigned char* lds, const Gemm g, const Sched& S, const Epi& E, const int tid_in) {
;     ...
;     f32x4 acc[2][2][4][2];
; #pragma unroll
;     for (int a = 0; a < 2; ++a)
; #pragma unroll
;         for (int b = 0; b < 2; ++b)
; #pragma unroll
;             for (int m = 0; m < 4; ++m)
; #pragma unroll
;                 for (int n = 0; n < 2; ++n) acc[a][b][m][n] = (f32x4){0.f, 0.f, 0.f, 0.f};
;     ...
;     for (;;) {
;         const bool has_next = S.next(ui + 1, nxt);
;         const char* nA = has_next ? (const char*)g.A + (size_t)nxt.pm * tstep : cA; const char* nB = has_next ? (const char*)g.Bt + (size_t)nxt.pn * tstep : cB;
;         for (int t = 0; t < nt; t += 2) {
;             const bool last = (t == nt - 2);
;             const char* a1 = cA + (size_t)(t + 1) * kstep;
;             const char* a2 = last ? nA : cA + (size_t)(t + 2) * kstep; const char* b2 = last ? nB : cB + (size_t)(t + 2) * kstep;
;             const char* a3 = a2 + kstep; const char* b3 = b2 + kstep;
.LBB0_706:
	v_mov_b32_e32 v123, 0
	s_andn2_b64 vcc, exec, s[12:13]
	v_mov_b32_e32 v122, v123
	v_mov_b32_e32 v121, v123
	v_mov_b32_e32 v120, v123
	v_mov_b32_e32 v127, v123
	v_mov_b32_e32 v126, v123
	v_mov_b32_e32 v125, v123
	v_mov_b32_e32 v124, v123
	v_mov_b32_e32 v111, v123
	v_mov_b32_e32 v110, v123
	v_mov_b32_e32 v109, v123
	v_mov_b32_e32 v108, v123
	v_mov_b32_e32 v107, v123
	v_mov_b32_e32 v106, v123
	v_mov_b32_e32 v105, v123
	v_mov_b32_e32 v104, v123
	v_mov_b32_e32 v95, v123
	v_mov_b32_e32 v94, v123
	v_mov_b32_e32 v93, v123
	v_mov_b32_e32 v92, v123
	v_mov_b32_e32 v91, v123
	v_mov_b32_e32 v90, v123
	v_mov_b32_e32 v89, v123
	v_mov_b32_e32 v88, v123
	v_mov_b32_e32 v79, v123
	v_mov_b32_e32 v78, v123
	v_mov_b32_e32 v77, v123
	v_mov_b32_e32 v76, v123
	v_mov_b32_e32 v75, v123
	v_mov_b32_e32 v74, v123
	v_mov_b32_e32 v73, v123
	v_mov_b32_e32 v72, v123
	v_mov_b32_e32 v119, v123
	v_mov_b32_e32 v118, v123
	v_mov_b32_e32 v117, v123
	v_mov_b32_e32 v116, v123
	v_mov_b32_e32 v115, v123
	v_mov_b32_e32 v114, v123
	v_mov_b32_e32 v113, v123
	v_mov_b32_e32 v112, v123
	v_mov_b32_e32 v103, v123
	v_mov_b32_e32 v102, v123
	v_mov_b32_e32 v101, v123
	v_mov_b32_e32 v100, v123
	v_mov_b32_e32 v99, v123
	v_mov_b32_e32 v98, v123
	v_mov_b32_e32 v97, v123
	v_mov_b32_e32 v96, v123
	v_mov_b32_e32 v87, v123
	v_mov_b32_e32 v86, v123
	v_mov_b32_e32 v85, v123
	v_mov_b32_e32 v84, v123
	v_mov_b32_e32 v83, v123
	v_mov_b32_e32 v82, v123
	v_mov_b32_e32 v81, v123
	v_mov_b32_e32 v80, v123
	v_mov_b32_e32 v71, v123
	v_mov_b32_e32 v70, v123
	v_mov_b32_e32 v69, v123
	v_mov_b32_e32 v68, v123
	v_mov_b32_e32 v67, v123
	v_mov_b32_e32 v66, v123
	v_mov_b32_e32 v65, v123
	v_mov_b32_e32 v64, v123
	v_mov_b32_e32 v63, v123
	v_mov_b32_e32 v62, v123
	v_mov_b32_e32 v61, v123
	v_mov_b32_e32 v60, v123
	v_mov_b32_e32 v59, v123
	v_mov_b32_e32 v58, v123
	v_mov_b32_e32 v57, v123
	v_mov_b32_e32 v56, v123
	v_mov_b32_e32 v47, v123
	v_mov_b32_e32 v46, v123
	v_mov_b32_e32 v45, v123
	v_mov_b32_e32 v44, v123
	v_mov_b32_e32 v43, v123
	v_mov_b32_e32 v42, v123
	v_mov_b32_e32 v41, v123
	v_mov_b32_e32 v40, v123
	v_mov_b32_e32 v31, v123
	v_mov_b32_e32 v30, v123
	v_mov_b32_e32 v29, v123
	v_mov_b32_e32 v28, v123
	v_mov_b32_e32 v27, v123
	v_mov_b32_e32 v26, v123
	v_mov_b32_e32 v25, v123
	v_mov_b32_e32 v24, v123
	v_mov_b32_e32 v15, v123
	v_mov_b32_e32 v14, v123
	v_mov_b32_e32 v13, v123
	v_mov_b32_e32 v12, v123
	v_mov_b32_e32 v11, v123
	v_mov_b32_e32 v10, v123
	v_mov_b32_e32 v9, v123
	v_mov_b32_e32 v8, v123
	v_mov_b32_e32 v55, v123
	v_mov_b32_e32 v54, v123
	v_mov_b32_e32 v53, v123
	v_mov_b32_e32 v52, v123
	v_mov_b32_e32 v51, v123
	v_mov_b32_e32 v50, v123
	v_mov_b32_e32 v49, v123
	v_mov_b32_e32 v48, v123
	v_mov_b32_e32 v39, v123
	v_mov_b32_e32 v38, v123
	v_mov_b32_e32 v37, v123
	v_mov_b32_e32 v36, v123
	v_mov_b32_e32 v35, v123
	v_mov_b32_e32 v34, v123
	v_mov_b32_e32 v33, v123
	v_mov_b32_e32 v32, v123
	v_mov_b32_e32 v23, v123
	v_mov_b32_e32 v22, v123
	v_mov_b32_e32 v21, v123
	v_mov_b32_e32 v20, v123
	v_mov_b32_e32 v19, v123
	v_mov_b32_e32 v18, v123
	v_mov_b32_e32 v17, v123
	v_mov_b32_e32 v16, v123
	v_mov_b32_e32 v7, v123
	v_mov_b32_e32 v6, v123
	v_mov_b32_e32 v5, v123
	v_mov_b32_e32 v4, v123
	v_mov_b32_e32 v3, v123
	v_mov_b32_e32 v2, v123
	v_mov_b32_e32 v1, v123
	v_mov_b32_e32 v0, v123
	s_cbranch_vccnz .LBB0_710
	s_add_u32 s18, s18, 0x80
	s_addc_u32 s19, s19, 0
	s_add_u32 s47, s20, 0x100
	v_mov_b32_e32 v0, 0
	s_addc_u32 s48, s21, 0
	s_mov_b32 s20, 0
	v_mov_b32_e32 v1, v0
	v_mov_b32_e32 v2, v0
	v_mov_b32_e32 v3, v0
	v_mov_b32_e32 v4, v0
	v_mov_b32_e32 v5, v0
	v_mov_b32_e32 v6, v0
	v_mov_b32_e32 v7, v0
	v_mov_b32_e32 v16, v0
	v_mov_b32_e32 v17, v0
	v_mov_b32_e32 v18, v0
	v_mov_b32_e32 v19, v0
	v_mov_b32_e32 v20, v0
	v_mov_b32_e32 v21, v0
	v_mov_b32_e32 v22, v0
	v_mov_b32_e32 v23, v0
	v_mov_b32_e32 v32, v0
	v_mov_b32_e32 v33, v0
	v_mov_b32_e32 v34, v0
	v_mov_b32_e32 v35, v0
	v_mov_b32_e32 v36, v0
	v_mov_b32_e32 v37, v0
	v_mov_b32_e32 v38, v0
	v_mov_b32_e32 v39, v0
	v_mov_b32_e32 v48, v0
	v_mov_b32_e32 v49, v0
	v_mov_b32_e32 v50, v0
	v_mov_b32_e32 v51, v0
	v_mov_b32_e32 v52, v0
	v_mov_b32_e32 v53, v0
	v_mov_b32_e32 v54, v0
	v_mov_b32_e32 v55, v0
	v_mov_b32_e32 v8, v0
	v_mov_b32_e32 v9, v0
	v_mov_b32_e32 v10, v0
	v_mov_b32_e32 v11, v0
	v_mov_b32_e32 v12, v0
	v_mov_b32_e32 v13, v0
	v_mov_b32_e32 v14, v0
	v_mov_b32_e32 v15, v0
	v_mov_b32_e32 v24, v0
	v_mov_b32_e32 v25, v0
	v_mov_b32_e32 v26, v0
	v_mov_b32_e32 v27, v0
	v_mov_b32_e32 v28, v0
	v_mov_b32_e32 v29, v0
	v_mov_b32_e32 v30, v0
	v_mov_b32_e32 v31, v0
	v_mov_b32_e32 v40, v0
	v_mov_b32_e32 v41, v0
	v_mov_b32_e32 v42, v0
	v_mov_b32_e32 v43, v0
	v_mov_b32_e32 v44, v0
	v_mov_b32_e32 v45, v0
	v_mov_b32_e32 v46, v0
	v_mov_b32_e32 v47, v0
	v_mov_b32_e32 v56, v0
	v_mov_b32_e32 v57, v0
	v_mov_b32_e32 v58, v0
	v_mov_b32_e32 v59, v0
	v_mov_b32_e32 v60, v0
	v_mov_b32_e32 v61, v0
	v_mov_b32_e32 v62, v0
	v_mov_b32_e32 v63, v0
	v_mov_b32_e32 v64, v0
	v_mov_b32_e32 v65, v0
	v_mov_b32_e32 v66, v0
	v_mov_b32_e32 v67, v0
	v_mov_b32_e32 v68, v0
	v_mov_b32_e32 v69, v0
	v_mov_b32_e32 v70, v0
	v_mov_b32_e32 v71, v0
	v_mov_b32_e32 v80, v0
	v_mov_b32_e32 v81, v0
	v_mov_b32_e32 v82, v0
	v_mov_b32_e32 v83, v0
	v_mov_b32_e32 v84, v0
	v_mov_b32_e32 v85, v0
	v_mov_b32_e32 v86, v0
	v_mov_b32_e32 v87, v0
	v_mov_b32_e32 v96, v0
	v_mov_b32_e32 v97, v0
	v_mov_b32_e32 v98, v0
	v_mov_b32_e32 v99, v0
	v_mov_b32_e32 v100, v0
	v_mov_b32_e32 v101, v0
	v_mov_b32_e32 v102, v0
	v_mov_b32_e32 v103, v0
	v_mov_b32_e32 v112, v0
	v_mov_b32_e32 v113, v0
	v_mov_b32_e32 v114, v0
	v_mov_b32_e32 v115, v0
	v_mov_b32_e32 v116, v0
	v_mov_b32_e32 v117, v0
	v_mov_b32_e32 v118, v0
	v_mov_b32_e32 v119, v0
	v_mov_b32_e32 v72, v0
	v_mov_b32_e32 v73, v0
	v_mov_b32_e32 v74, v0
	v_mov_b32_e32 v75, v0
	v_mov_b32_e32 v76, v0
	v_mov_b32_e32 v77, v0
	v_mov_b32_e32 v78, v0
	v_mov_b32_e32 v79, v0
	v_mov_b32_e32 v88, v0
	v_mov_b32_e32 v89, v0
	v_mov_b32_e32 v90, v0
	v_mov_b32_e32 v91, v0
	v_mov_b32_e32 v92, v0
	v_mov_b32_e32 v93, v0
	v_mov_b32_e32 v94, v0
	v_mov_b32_e32 v95, v0
	v_mov_b32_e32 v104, v0
	v_mov_b32_e32 v105, v0
	v_mov_b32_e32 v106, v0
	v_mov_b32_e32 v107, v0
	v_mov_b32_e32 v108, v0
	v_mov_b32_e32 v109, v0
	v_mov_b32_e32 v110, v0
	v_mov_b32_e32 v111, v0
	v_mov_b32_e32 v124, v0
	v_mov_b32_e32 v125, v0
	v_mov_b32_e32 v126, v0
	v_mov_b32_e32 v127, v0
	v_mov_b32_e32 v120, v0
	v_mov_b32_e32 v121, v0
	v_mov_b32_e32 v122, v0
	v_mov_b32_e32 v123, v0
	.p2align	6

; template <class Epi, class Sched, bool ALIGN_EPI = false, bool SP2 = false>
; __device__ __forceinline__ void gemm_phase(PG8_LAS unsigned char* lds, const Gemm g, const Sched& S, const Epi& E, const int tid_in) {
;     ...
;     f32x4 acc[2][2][4][2];
; #pragma unroll
;     for (int a = 0; a < 2; ++a)
; #pragma unroll
;         for (int b = 0; b < 2; ++b)
; #pragma unroll
;             for (int m = 0; m < 4; ++m)
; #pragma unroll
;                 for (int n = 0; n < 2; ++n) acc[a][b][m][n] = (f32x4){0.f, 0.f, 0.f, 0.f};
;     ...
;     for (;;) {
;         const bool has_next = S.next(ui + 1, nxt);
;         const char* nA = has_next ? (const char*)g.A + (size_t)nxt.pm * tstep : cA; const char* nB = has_next ? (const char*)g.Bt + (size_t)nxt.pn * tstep : cB;
;         for (int t = 0; t < nt; t += 2) {
;             const bool last = (t == nt - 2);
;             const char* a1 = cA + (size_t)(t + 1) * kstep;
;             const char* a2 = last ? nA : cA + (size_t)(t + 2) * kstep; const char* b2 = last ? nB : cB + (size_t)(t + 2) * kstep;
;             const char* a3 = a2 + kstep; const char* b3 = b2 + kstep;
.LBB0_729:
	v_mov_b32_e32 v123, 0
	s_andn2_b64 vcc, exec, s[10:11]
	v_mov_b32_e32 v122, v123
	v_mov_b32_e32 v121, v123
	v_mov_b32_e32 v120, v123
	v_mov_b32_e32 v127, v123
	v_mov_b32_e32 v126, v123
	v_mov_b32_e32 v125, v123
	v_mov_b32_e32 v124, v123
	v_mov_b32_e32 v111, v123
	v_mov_b32_e32 v110, v123
	v_mov_b32_e32 v109, v123
	v_mov_b32_e32 v108, v123
	v_mov_b32_e32 v107, v123
	v_mov_b32_e32 v106, v123
	v_mov_b32_e32 v105, v123
	v_mov_b32_e32 v104, v123
	v_mov_b32_e32 v95, v123
	v_mov_b32_e32 v94, v123
	v_mov_b32_e32 v93, v123
	v_mov_b32_e32 v92, v123
	v_mov_b32_e32 v91, v123
	v_mov_b32_e32 v90, v123
	v_mov_b32_e32 v89, v123
	v_mov_b32_e32 v88, v123
	v_mov_b32_e32 v79, v123
	v_mov_b32_e32 v78, v123
	v_mov_b32_e32 v77, v123
	v_mov_b32_e32 v76, v123
	v_mov_b32_e32 v75, v123
	v_mov_b32_e32 v74, v123
	v_mov_b32_e32 v73, v123
	v_mov_b32_e32 v72, v123
	v_mov_b32_e32 v119, v123
	v_mov_b32_e32 v118, v123
	v_mov_b32_e32 v117, v123
	v_mov_b32_e32 v116, v123
	v_mov_b32_e32 v115, v123
	v_mov_b32_e32 v114, v123
	v_mov_b32_e32 v113, v123
	v_mov_b32_e32 v112, v123
	v_mov_b32_e32 v103, v123
	v_mov_b32_e32 v102, v123
	v_mov_b32_e32 v101, v123
	v_mov_b32_e32 v100, v123
	v_mov_b32_e32 v99, v123
	v_mov_b32_e32 v98, v123
	v_mov_b32_e32 v97, v123
	v_mov_b32_e32 v96, v123
	v_mov_b32_e32 v87, v123
	v_mov_b32_e32 v86, v123
	v_mov_b32_e32 v85, v123
	v_mov_b32_e32 v84, v123
	v_mov_b32_e32 v83, v123
	v_mov_b32_e32 v82, v123
	v_mov_b32_e32 v81, v123
	v_mov_b32_e32 v80, v123
	v_mov_b32_e32 v71, v123
	v_mov_b32_e32 v70, v123
	v_mov_b32_e32 v69, v123
	v_mov_b32_e32 v68, v123
	v_mov_b32_e32 v67, v123
	v_mov_b32_e32 v66, v123
	v_mov_b32_e32 v65, v123
	v_mov_b32_e32 v64, v123
	v_mov_b32_e32 v63, v123
	v_mov_b32_e32 v62, v123
	v_mov_b32_e32 v61, v123
	v_mov_b32_e32 v60, v123
	v_mov_b32_e32 v59, v123
	v_mov_b32_e32 v58, v123
	v_mov_b32_e32 v57, v123
	v_mov_b32_e32 v56, v123
	v_mov_b32_e32 v47, v123
	v_mov_b32_e32 v46, v123
	v_mov_b32_e32 v45, v123
	v_mov_b32_e32 v44, v123
	v_mov_b32_e32 v43, v123
	v_mov_b32_e32 v42, v123
	v_mov_b32_e32 v41, v123
	v_mov_b32_e32 v40, v123
	v_mov_b32_e32 v31, v123
	v_mov_b32_e32 v30, v123
	v_mov_b32_e32 v29, v123
	v_mov_b32_e32 v28, v123
	v_mov_b32_e32 v27, v123
	v_mov_b32_e32 v26, v123
	v_mov_b32_e32 v25, v123
	v_mov_b32_e32 v24, v123
	v_mov_b32_e32 v15, v123
	v_mov_b32_e32 v14, v123
	v_mov_b32_e32 v13, v123
	v_mov_b32_e32 v12, v123
	v_mov_b32_e32 v11, v123
	v_mov_b32_e32 v10, v123
	v_mov_b32_e32 v9, v123
	v_mov_b32_e32 v8, v123
	v_mov_b32_e32 v55, v123
	v_mov_b32_e32 v54, v123
	v_mov_b32_e32 v53, v123
	v_mov_b32_e32 v52, v123
	v_mov_b32_e32 v51, v123
	v_mov_b32_e32 v50, v123
	v_mov_b32_e32 v49, v123
	v_mov_b32_e32 v48, v123
	v_mov_b32_e32 v39, v123
	v_mov_b32_e32 v38, v123
	v_mov_b32_e32 v37, v123
	v_mov_b32_e32 v36, v123
	v_mov_b32_e32 v35, v123
	v_mov_b32_e32 v34, v123
	v_mov_b32_e32 v33, v123
	v_mov_b32_e32 v32, v123
	v_mov_b32_e32 v23, v123
	v_mov_b32_e32 v22, v123
	v_mov_b32_e32 v21, v123
	v_mov_b32_e32 v20, v123
	v_mov_b32_e32 v19, v123
	v_mov_b32_e32 v18, v123
	v_mov_b32_e32 v17, v123
	v_mov_b32_e32 v16, v123
	v_mov_b32_e32 v7, v123
	v_mov_b32_e32 v6, v123
	v_mov_b32_e32 v5, v123
	v_mov_b32_e32 v4, v123
	v_mov_b32_e32 v3, v123
	v_mov_b32_e32 v2, v123
	v_mov_b32_e32 v1, v123
	v_mov_b32_e32 v0, v123
	s_cbranch_vccnz .LBB0_733
	s_add_u32 s16, s16, 0x80
	s_addc_u32 s17, s17, 0
	s_add_u32 s42, s18, 0x100
	v_mov_b32_e32 v0, 0
	s_addc_u32 s43, s19, 0
	s_mov_b32 s18, 0
	v_mov_b32_e32 v1, v0
	v_mov_b32_e32 v2, v0
	v_mov_b32_e32 v3, v0
	v_mov_b32_e32 v4, v0
	v_mov_b32_e32 v5, v0
	v_mov_b32_e32 v6, v0
	v_mov_b32_e32 v7, v0
	v_mov_b32_e32 v16, v0
	v_mov_b32_e32 v17, v0
	v_mov_b32_e32 v18, v0
	v_mov_b32_e32 v19, v0
	v_mov_b32_e32 v20, v0
	v_mov_b32_e32 v21, v0
	v_mov_b32_e32 v22, v0
	v_mov_b32_e32 v23, v0
	v_mov_b32_e32 v32, v0
	v_mov_b32_e32 v33, v0
	v_mov_b32_e32 v34, v0
	v_mov_b32_e32 v35, v0
	v_mov_b32_e32 v36, v0
	v_mov_b32_e32 v37, v0
	v_mov_b32_e32 v38, v0
	v_mov_b32_e32 v39, v0
	v_mov_b32_e32 v48, v0
	v_mov_b32_e32 v49, v0
	v_mov_b32_e32 v50, v0
	v_mov_b32_e32 v51, v0
	v_mov_b32_e32 v52, v0
	v_mov_b32_e32 v53, v0
	v_mov_b32_e32 v54, v0
	v_mov_b32_e32 v55, v0
	v_mov_b32_e32 v8, v0
	v_mov_b32_e32 v9, v0
	v_mov_b32_e32 v10, v0
	v_mov_b32_e32 v11, v0
	v_mov_b32_e32 v12, v0
	v_mov_b32_e32 v13, v0
	v_mov_b32_e32 v14, v0
	v_mov_b32_e32 v15, v0
	v_mov_b32_e32 v24, v0
	v_mov_b32_e32 v25, v0
	v_mov_b32_e32 v26, v0
	v_mov_b32_e32 v27, v0
	v_mov_b32_e32 v28, v0
	v_mov_b32_e32 v29, v0
	v_mov_b32_e32 v30, v0
	v_mov_b32_e32 v31, v0
	v_mov_b32_e32 v40, v0
	v_mov_b32_e32 v41, v0
	v_mov_b32_e32 v42, v0
	v_mov_b32_e32 v43, v0
	v_mov_b32_e32 v44, v0
	v_mov_b32_e32 v45, v0
	v_mov_b32_e32 v46, v0
	v_mov_b32_e32 v47, v0
	v_mov_b32_e32 v56, v0
	v_mov_b32_e32 v57, v0
	v_mov_b32_e32 v58, v0
	v_mov_b32_e32 v59, v0
	v_mov_b32_e32 v60, v0
	v_mov_b32_e32 v61, v0
	v_mov_b32_e32 v62, v0
	v_mov_b32_e32 v63, v0
	v_mov_b32_e32 v64, v0
	v_mov_b32_e32 v65, v0
	v_mov_b32_e32 v66, v0
	v_mov_b32_e32 v67, v0
	v_mov_b32_e32 v68, v0
	v_mov_b32_e32 v69, v0
	v_mov_b32_e32 v70, v0
	v_mov_b32_e32 v71, v0
	v_mov_b32_e32 v80, v0
	v_mov_b32_e32 v81, v0
	v_mov_b32_e32 v82, v0
	v_mov_b32_e32 v83, v0
	v_mov_b32_e32 v84, v0
	v_mov_b32_e32 v85, v0
	v_mov_b32_e32 v86, v0
	v_mov_b32_e32 v87, v0
	v_mov_b32_e32 v96, v0
	v_mov_b32_e32 v97, v0
	v_mov_b32_e32 v98, v0
	v_mov_b32_e32 v99, v0
	v_mov_b32_e32 v100, v0
	v_mov_b32_e32 v101, v0
	v_mov_b32_e32 v102, v0
	v_mov_b32_e32 v103, v0
	v_mov_b32_e32 v112, v0
	v_mov_b32_e32 v113, v0
	v_mov_b32_e32 v114, v0
	v_mov_b32_e32 v115, v0
	v_mov_b32_e32 v116, v0
	v_mov_b32_e32 v117, v0
	v_mov_b32_e32 v118, v0
	v_mov_b32_e32 v119, v0
	v_mov_b32_e32 v72, v0
	v_mov_b32_e32 v73, v0
	v_mov_b32_e32 v74, v0
	v_mov_b32_e32 v75, v0
	v_mov_b32_e32 v76, v0
	v_mov_b32_e32 v77, v0
	v_mov_b32_e32 v78, v0
	v_mov_b32_e32 v79, v0
	v_mov_b32_e32 v88, v0
	v_mov_b32_e32 v89, v0
	v_mov_b32_e32 v90, v0
	v_mov_b32_e32 v91, v0
	v_mov_b32_e32 v92, v0
	v_mov_b32_e32 v93, v0
	v_mov_b32_e32 v94, v0
	v_mov_b32_e32 v95, v0
	v_mov_b32_e32 v104, v0
	v_mov_b32_e32 v105, v0
	v_mov_b32_e32 v106, v0
	v_mov_b32_e32 v107, v0
	v_mov_b32_e32 v108, v0
	v_mov_b32_e32 v109, v0
	v_mov_b32_e32 v110, v0
	v_mov_b32_e32 v111, v0
	v_mov_b32_e32 v124, v0
	v_mov_b32_e32 v125, v0
	v_mov_b32_e32 v126, v0
	v_mov_b32_e32 v127, v0
	v_mov_b32_e32 v120, v0
	v_mov_b32_e32 v121, v0
	v_mov_b32_e32 v122, v0
	v_mov_b32_e32 v123, v0
	.p2align	6

; template <class Epi, class Sched, bool ALIGN_EPI = false, bool SP2 = false>
; __device__ __forceinline__ void gemm_phase(PG8_LAS unsigned char* lds, const Gemm g, const Sched& S, const Epi& E, const int tid_in) {
;     ...
;         for (int t = 0; t < nt; t += 2) {
;             const bool last = (t == nt - 2);
;             const char* a1 = cA + (size_t)(t + 1) * kstep;
;             const char* a2 = last ? nA : cA + (size_t)(t + 2) * kstep; const char* b2 = last ? nB : cB + (size_t)(t + 2) * kstep;
;             const char* a3 = a2 + kstep; const char* b3 = b2 + kstep;
;     ...
; #pragma unroll
;         for (int a = 0; a < 2; ++a)
; #pragma unroll
;             for (int b = 0; b < 2; ++b)
; #pragma unroll
;                 for (int m = 0; m < 4; ++m)
; #pragma unroll
;                     for (int n = 0; n < 2; ++n) acc[a][b][m][n] = (f32x4){0.f, 0.f, 0.f, 0.f};
;         cur = nxt; cA = nA; cB = nB; ++ui;
.LBB0_788:
	s_add_u32 s22, s22, 0x80
	s_addc_u32 s23, s23, 0
	s_add_u32 s58, s38, 0x100
	v_mov_b32_e32 v0, 0
	s_addc_u32 s66, s39, 0
	s_mov_b32 s38, 0
	v_mov_b32_e32 v1, v0
	v_mov_b32_e32 v2, v0
	v_mov_b32_e32 v3, v0
	v_mov_b32_e32 v4, v0
	v_mov_b32_e32 v5, v0
	v_mov_b32_e32 v6, v0
	v_mov_b32_e32 v7, v0
	v_mov_b32_e32 v16, v0
	v_mov_b32_e32 v17, v0
	v_mov_b32_e32 v18, v0
	v_mov_b32_e32 v19, v0
	v_mov_b32_e32 v20, v0
	v_mov_b32_e32 v21, v0
	v_mov_b32_e32 v22, v0
	v_mov_b32_e32 v23, v0
	v_mov_b32_e32 v32, v0
	v_mov_b32_e32 v33, v0
	v_mov_b32_e32 v34, v0
	v_mov_b32_e32 v35, v0
	v_mov_b32_e32 v36, v0
	v_mov_b32_e32 v37, v0
	v_mov_b32_e32 v38, v0
	v_mov_b32_e32 v39, v0
	v_mov_b32_e32 v48, v0
	v_mov_b32_e32 v49, v0
	v_mov_b32_e32 v50, v0
	v_mov_b32_e32 v51, v0
	v_mov_b32_e32 v52, v0
	v_mov_b32_e32 v53, v0
	v_mov_b32_e32 v54, v0
	v_mov_b32_e32 v55, v0
	v_mov_b32_e32 v8, v0
	v_mov_b32_e32 v9, v0
	v_mov_b32_e32 v10, v0
	v_mov_b32_e32 v11, v0
	v_mov_b32_e32 v12, v0
	v_mov_b32_e32 v13, v0
	v_mov_b32_e32 v14, v0
	v_mov_b32_e32 v15, v0
	v_mov_b32_e32 v24, v0
	v_mov_b32_e32 v25, v0
	v_mov_b32_e32 v26, v0
	v_mov_b32_e32 v27, v0
	v_mov_b32_e32 v28, v0
	v_mov_b32_e32 v29, v0
	v_mov_b32_e32 v30, v0
	v_mov_b32_e32 v31, v0
	v_mov_b32_e32 v40, v0
	v_mov_b32_e32 v41, v0
	v_mov_b32_e32 v42, v0
	v_mov_b32_e32 v43, v0
	v_mov_b32_e32 v44, v0
	v_mov_b32_e32 v45, v0
	v_mov_b32_e32 v46, v0
	v_mov_b32_e32 v47, v0
	v_mov_b32_e32 v56, v0
	v_mov_b32_e32 v57, v0
	v_mov_b32_e32 v58, v0
	v_mov_b32_e32 v59, v0
	v_mov_b32_e32 v60, v0
	v_mov_b32_e32 v61, v0
	v_mov_b32_e32 v62, v0
	v_mov_b32_e32 v63, v0
	v_mov_b32_e32 v64, v0
	v_mov_b32_e32 v65, v0
	v_mov_b32_e32 v66, v0
	v_mov_b32_e32 v67, v0
	v_mov_b32_e32 v68, v0
	v_mov_b32_e32 v69, v0
	v_mov_b32_e32 v70, v0
	v_mov_b32_e32 v71, v0
	v_mov_b32_e32 v80, v0
	v_mov_b32_e32 v81, v0
	v_mov_b32_e32 v82, v0
	v_mov_b32_e32 v83, v0
	v_mov_b32_e32 v84, v0
	v_mov_b32_e32 v85, v0
	v_mov_b32_e32 v86, v0
	v_mov_b32_e32 v87, v0
	v_mov_b32_e32 v96, v0
	v_mov_b32_e32 v97, v0
	v_mov_b32_e32 v98, v0
	v_mov_b32_e32 v99, v0
	v_mov_b32_e32 v100, v0
	v_mov_b32_e32 v101, v0
	v_mov_b32_e32 v102, v0
	v_mov_b32_e32 v103, v0
	v_mov_b32_e32 v112, v0
	v_mov_b32_e32 v113, v0
	v_mov_b32_e32 v114, v0
	v_mov_b32_e32 v115, v0
	v_mov_b32_e32 v116, v0
	v_mov_b32_e32 v117, v0
	v_mov_b32_e32 v118, v0
	v_mov_b32_e32 v119, v0
	v_mov_b32_e32 v72, v0
	v_mov_b32_e32 v73, v0
	v_mov_b32_e32 v74, v0
	v_mov_b32_e32 v75, v0
	v_mov_b32_e32 v76, v0
	v_mov_b32_e32 v77, v0
	v_mov_b32_e32 v78, v0
	v_mov_b32_e32 v79, v0
	v_mov_b32_e32 v88, v0
	v_mov_b32_e32 v89, v0
	v_mov_b32_e32 v90, v0
	v_mov_b32_e32 v91, v0
	v_mov_b32_e32 v92, v0
	v_mov_b32_e32 v93, v0
	v_mov_b32_e32 v94, v0
	v_mov_b32_e32 v95, v0
	v_mov_b32_e32 v104, v0
	v_mov_b32_e32 v105, v0
	v_mov_b32_e32 v106, v0
	v_mov_b32_e32 v107, v0
	v_mov_b32_e32 v108, v0
	v_mov_b32_e32 v109, v0
	v_mov_b32_e32 v110, v0
	v_mov_b32_e32 v111, v0
	v_mov_b32_e32 v120, v0
	v_mov_b32_e32 v121, v0
	v_mov_b32_e32 v122, v0
	v_mov_b32_e32 v123, v0
	v_mov_b32_e32 v124, v0
	v_mov_b32_e32 v125, v0
	v_mov_b32_e32 v126, v0
	v_mov_b32_e32 v127, v0
	.p2align	6
